# GEMM K loops without the mid-cluster s_setprio 0/1 pair
# baseline (speedup 1.0000x reference)
.LBB0_130:
	s_ashr_i32 s13, s12, 31
	s_lshl_b64 s[14:15], s[12:13], 19
	v_readlane_b32 s16, v254, 39
	v_readlane_b32 s17, v254, 40
	s_add_u32 s14, s16, s14
	s_addc_u32 s15, s17, s15
	s_and_b64 s[16:17], s[0:1], exec
	s_cselect_b32 s13, s15, s19
	s_cselect_b32 s42, s14, s18
	s_ashr_i32 s11, s10, 31
	s_lshl_b64 s[16:17], s[10:11], 19
	s_add_u32 s16, s24, s16
	s_addc_u32 s17, s25, s17
	s_and_b64 s[22:23], s[0:1], exec
	s_cselect_b32 s11, s17, s21
	s_cselect_b32 s43, s16, s20
	s_add_u32 s18, s18, 0x40080
	s_addc_u32 s19, s19, 0
	s_add_u32 s44, s20, 0x100
	s_addc_u32 s45, s21, 0
	s_mov_b32 s46, -2
	ds_read_b128 v[152:155], v148
	ds_read_b128 v[156:159], v148 offset:1024
	ds_read_b128 v[160:163], v148 offset:2048
	ds_read_b128 v[164:167], v148 offset:3072
	ds_read_b128 v[168:171], v149
	ds_read_b128 v[172:175], v149 offset:1024
	ds_read_b128 v[176:179], v149 offset:2048
	ds_read_b128 v[180:183], v149 offset:3072
	s_add_u32 s20, s18, 0xfffc0080
	s_addc_u32 s21, s19, -1
	s_cmp_eq_u32 s46, 12
	s_cselect_b32 s23, s13, s21
	s_cselect_b32 s22, s42, s20
	s_cselect_b32 s21, s11, s45
	s_cselect_b32 s20, s43, s44
	s_add_i32 m0, s9, 0xc000
	ds_read_b128 v[184:187], v150
	ds_read_b128 v[188:191], v150 offset:1024
	ds_read_b128 v[192:195], v150 offset:2048
	ds_read_b128 v[196:199], v150 offset:3072
	ds_read_b128 v[200:203], v150 offset:4096
	ds_read_b128 v[204:207], v150 offset:5120
	ds_read_b128 v[208:211], v150 offset:6144
	ds_read_b128 v[212:215], v150 offset:7168
	global_load_lds_dwordx4 v136, s[18:19]
	s_add_i32 m0, s9, 0xe000
	s_nop 0
	global_load_lds_dwordx4 v138, s[18:19]
	s_waitcnt vmcnt(8)
	s_waitcnt lgkmcnt(0)
	s_barrier
	s_setprio 1
	s_waitcnt lgkmcnt(0)
	v_mfma_f32_16x16x32_bf16 v[124:127], v[152:155], v[184:187], 0
	v_mfma_f32_16x16x32_bf16 v[120:123], v[160:163], v[184:187], 0
	v_mfma_f32_16x16x32_bf16 v[116:119], v[152:155], v[192:195], 0
	v_mfma_f32_16x16x32_bf16 v[112:115], v[160:163], v[192:195], 0
	v_mfma_f32_16x16x32_bf16 v[100:103], v[152:155], v[200:203], 0
	v_mfma_f32_16x16x32_bf16 v[96:99], v[160:163], v[200:203], 0
	v_mfma_f32_16x16x32_bf16 v[84:87], v[152:155], v[208:211], 0
	v_mfma_f32_16x16x32_bf16 v[80:83], v[160:163], v[208:211], 0
	v_mfma_f32_16x16x32_bf16 v[124:127], v[156:159], v[188:191], v[124:127]
	v_mfma_f32_16x16x32_bf16 v[120:123], v[164:167], v[188:191], v[120:123]
	v_mfma_f32_16x16x32_bf16 v[116:119], v[156:159], v[196:199], v[116:119]
	v_mfma_f32_16x16x32_bf16 v[112:115], v[164:167], v[196:199], v[112:115]
	v_mfma_f32_16x16x32_bf16 v[100:103], v[156:159], v[204:207], v[100:103]
	v_mfma_f32_16x16x32_bf16 v[96:99], v[164:167], v[204:207], v[96:99]
	v_mfma_f32_16x16x32_bf16 v[84:87], v[156:159], v[212:215], v[84:87]
	v_mfma_f32_16x16x32_bf16 v[80:83], v[164:167], v[212:215], v[80:83]


	v_mfma_f32_16x16x32_bf16 v[108:111], v[168:171], v[184:187], 0
	v_mfma_f32_16x16x32_bf16 v[104:107], v[176:179], v[184:187], 0
	v_mfma_f32_16x16x32_bf16 v[92:95], v[168:171], v[192:195], 0
	v_mfma_f32_16x16x32_bf16 v[88:91], v[176:179], v[192:195], 0
	v_mfma_f32_16x16x32_bf16 v[76:79], v[168:171], v[200:203], 0
	v_mfma_f32_16x16x32_bf16 v[72:75], v[176:179], v[200:203], 0
	v_mfma_f32_16x16x32_bf16 v[68:71], v[168:171], v[208:211], 0
	v_mfma_f32_16x16x32_bf16 v[64:67], v[176:179], v[208:211], 0
	v_mfma_f32_16x16x32_bf16 v[108:111], v[172:175], v[188:191], v[108:111]
	v_mfma_f32_16x16x32_bf16 v[104:107], v[180:183], v[188:191], v[104:107]
	v_mfma_f32_16x16x32_bf16 v[92:95], v[172:175], v[196:199], v[92:95]
	v_mfma_f32_16x16x32_bf16 v[88:91], v[180:183], v[196:199], v[88:91]
	v_mfma_f32_16x16x32_bf16 v[76:79], v[172:175], v[204:207], v[76:79]
	v_mfma_f32_16x16x32_bf16 v[72:75], v[180:183], v[204:207], v[72:75]
	v_mfma_f32_16x16x32_bf16 v[68:71], v[172:175], v[212:215], v[68:71]
	v_mfma_f32_16x16x32_bf16 v[64:67], v[180:183], v[212:215], v[64:67]
	s_setprio 0
	s_barrier
	s_add_i32 s47, s38, s26
	s_mov_b32 m0, s47
	ds_read_b128 v[184:187], v150 offset:16384
	ds_read_b128 v[188:191], v150 offset:17408
	ds_read_b128 v[192:195], v150 offset:18432
	ds_read_b128 v[196:199], v150 offset:19456
	ds_read_b128 v[200:203], v150 offset:20480
	ds_read_b128 v[204:207], v150 offset:21504
	ds_read_b128 v[208:211], v150 offset:22528
	ds_read_b128 v[212:215], v150 offset:23552
	global_load_lds_dwordx4 v132, s[20:21]
	s_add_i32 m0, s47, 0x2000
	s_add_u32 s48, s20, 0x40000
	s_addc_u32 s49, s21, 0
	s_add_i32 s47, s39, s26
	global_load_lds_dwordx4 v128, s[20:21]
	s_mov_b32 m0, s47
	s_nop 0
	global_load_lds_dwordx4 v132, s[48:49]
	s_add_i32 m0, s47, 0x2000
	s_nop 0
	global_load_lds_dwordx4 v128, s[48:49]
	s_mov_b32 m0, s9
	s_nop 0
	global_load_lds_dwordx4 v134, s[22:23]
	s_mov_b32 m0, s29
	s_nop 0
	global_load_lds_dwordx4 v130, s[22:23]
	s_add_u32 s84, s20, s4
	s_addc_u32 s85, s21, s5
	s_add_u32 s86, s22, s4
	s_addc_u32 s87, s23, s5
	s_waitcnt vmcnt(8)
	s_waitcnt lgkmcnt(0)
	s_barrier
	s_setprio 1
	s_waitcnt lgkmcnt(0)
	v_mfma_f32_16x16x32_bf16 v[60:63], v[152:155], v[184:187], 0
	v_mfma_f32_16x16x32_bf16 v[56:59], v[160:163], v[184:187], 0
	v_mfma_f32_16x16x32_bf16 v[52:55], v[152:155], v[192:195], 0
	v_mfma_f32_16x16x32_bf16 v[48:51], v[160:163], v[192:195], 0
	v_mfma_f32_16x16x32_bf16 v[36:39], v[152:155], v[200:203], 0
	v_mfma_f32_16x16x32_bf16 v[32:35], v[160:163], v[200:203], 0
	v_mfma_f32_16x16x32_bf16 v[20:23], v[152:155], v[208:211], 0
	v_mfma_f32_16x16x32_bf16 v[16:19], v[160:163], v[208:211], 0
	v_mfma_f32_16x16x32_bf16 v[60:63], v[156:159], v[188:191], v[60:63]
	v_mfma_f32_16x16x32_bf16 v[56:59], v[164:167], v[188:191], v[56:59]
	v_mfma_f32_16x16x32_bf16 v[52:55], v[156:159], v[196:199], v[52:55]
	v_mfma_f32_16x16x32_bf16 v[48:51], v[164:167], v[196:199], v[48:51]
	v_mfma_f32_16x16x32_bf16 v[36:39], v[156:159], v[204:207], v[36:39]
	v_mfma_f32_16x16x32_bf16 v[32:35], v[164:167], v[204:207], v[32:35]
	v_mfma_f32_16x16x32_bf16 v[20:23], v[156:159], v[212:215], v[20:23]
	v_mfma_f32_16x16x32_bf16 v[16:19], v[164:167], v[212:215], v[16:19]


	v_mfma_f32_16x16x32_bf16 v[44:47], v[168:171], v[184:187], 0
	v_mfma_f32_16x16x32_bf16 v[40:43], v[176:179], v[184:187], 0
	v_mfma_f32_16x16x32_bf16 v[28:31], v[168:171], v[192:195], 0
	v_mfma_f32_16x16x32_bf16 v[24:27], v[176:179], v[192:195], 0
	v_mfma_f32_16x16x32_bf16 v[12:15], v[168:171], v[200:203], 0
	v_mfma_f32_16x16x32_bf16 v[8:11], v[176:179], v[200:203], 0
	v_mfma_f32_16x16x32_bf16 v[4:7], v[168:171], v[208:211], 0
	v_mfma_f32_16x16x32_bf16 v[0:3], v[176:179], v[208:211], 0
	v_mfma_f32_16x16x32_bf16 v[44:47], v[172:175], v[188:191], v[44:47]
	v_mfma_f32_16x16x32_bf16 v[40:43], v[180:183], v[188:191], v[40:43]
	v_mfma_f32_16x16x32_bf16 v[28:31], v[172:175], v[196:199], v[28:31]
	v_mfma_f32_16x16x32_bf16 v[24:27], v[180:183], v[196:199], v[24:27]
	v_mfma_f32_16x16x32_bf16 v[12:15], v[172:175], v[204:207], v[12:15]
	v_mfma_f32_16x16x32_bf16 v[8:11], v[180:183], v[204:207], v[8:11]
	v_mfma_f32_16x16x32_bf16 v[4:7], v[172:175], v[212:215], v[4:7]
	v_mfma_f32_16x16x32_bf16 v[0:3], v[180:183], v[212:215], v[0:3]
	s_setprio 0
	s_barrier
	s_add_i32 s47, 0, 0x18000
	v_add_u32_e32 v151, s47, v146
	s_add_i32 s48, 0, 0x1c000
	ds_read_b128 v[152:155], v151
	ds_read_b128 v[156:159], v151 offset:1024
	ds_read_b128 v[160:163], v151 offset:2048
	ds_read_b128 v[164:167], v151 offset:3072
	v_add_u32_e32 v151, s48, v146
	ds_read_b128 v[168:171], v151
	ds_read_b128 v[172:175], v151 offset:1024
	ds_read_b128 v[176:179], v151 offset:2048
	ds_read_b128 v[180:183], v151 offset:3072
	s_add_u32 s22, s22, 0x40000
	s_addc_u32 s23, s23, 0
	s_mov_b32 m0, s30
	ds_read_b128 v[184:187], v150 offset:32768
	ds_read_b128 v[188:191], v150 offset:33792
	ds_read_b128 v[192:195], v150 offset:34816
	ds_read_b128 v[196:199], v150 offset:35840
	ds_read_b128 v[200:203], v150 offset:36864
	ds_read_b128 v[204:207], v150 offset:37888
	ds_read_b128 v[208:211], v150 offset:38912
	ds_read_b128 v[212:215], v150 offset:39936
	global_load_lds_dwordx4 v134, s[22:23]
	s_mov_b32 m0, s31
	s_nop 0
	global_load_lds_dwordx4 v130, s[22:23]
	s_waitcnt vmcnt(8)
	s_waitcnt lgkmcnt(0)
	s_barrier
	s_setprio 1
	s_waitcnt lgkmcnt(0)
	v_mfma_f32_16x16x32_bf16 v[124:127], v[152:155], v[184:187], v[124:127]
	v_mfma_f32_16x16x32_bf16 v[120:123], v[160:163], v[184:187], v[120:123]
	v_mfma_f32_16x16x32_bf16 v[116:119], v[152:155], v[192:195], v[116:119]
	v_mfma_f32_16x16x32_bf16 v[112:115], v[160:163], v[192:195], v[112:115]
	v_mfma_f32_16x16x32_bf16 v[100:103], v[152:155], v[200:203], v[100:103]
	v_mfma_f32_16x16x32_bf16 v[96:99], v[160:163], v[200:203], v[96:99]
	v_mfma_f32_16x16x32_bf16 v[84:87], v[152:155], v[208:211], v[84:87]
	v_mfma_f32_16x16x32_bf16 v[80:83], v[160:163], v[208:211], v[80:83]
	v_mfma_f32_16x16x32_bf16 v[124:127], v[156:159], v[188:191], v[124:127]
	v_mfma_f32_16x16x32_bf16 v[120:123], v[164:167], v[188:191], v[120:123]
	v_mfma_f32_16x16x32_bf16 v[116:119], v[156:159], v[196:199], v[116:119]
	v_mfma_f32_16x16x32_bf16 v[112:115], v[164:167], v[196:199], v[112:115]
	v_mfma_f32_16x16x32_bf16 v[100:103], v[156:159], v[204:207], v[100:103]
	v_mfma_f32_16x16x32_bf16 v[96:99], v[164:167], v[204:207], v[96:99]
	v_mfma_f32_16x16x32_bf16 v[84:87], v[156:159], v[212:215], v[84:87]
	v_mfma_f32_16x16x32_bf16 v[80:83], v[164:167], v[212:215], v[80:83]


	v_mfma_f32_16x16x32_bf16 v[108:111], v[168:171], v[184:187], v[108:111]
	v_mfma_f32_16x16x32_bf16 v[104:107], v[176:179], v[184:187], v[104:107]
	v_mfma_f32_16x16x32_bf16 v[92:95], v[168:171], v[192:195], v[92:95]
	v_mfma_f32_16x16x32_bf16 v[88:91], v[176:179], v[192:195], v[88:91]
	v_mfma_f32_16x16x32_bf16 v[76:79], v[168:171], v[200:203], v[76:79]
	v_mfma_f32_16x16x32_bf16 v[72:75], v[176:179], v[200:203], v[72:75]
	v_mfma_f32_16x16x32_bf16 v[68:71], v[168:171], v[208:211], v[68:71]
	v_mfma_f32_16x16x32_bf16 v[64:67], v[176:179], v[208:211], v[64:67]
	v_mfma_f32_16x16x32_bf16 v[108:111], v[172:175], v[188:191], v[108:111]
	v_mfma_f32_16x16x32_bf16 v[104:107], v[180:183], v[188:191], v[104:107]
	v_mfma_f32_16x16x32_bf16 v[92:95], v[172:175], v[196:199], v[92:95]
	v_mfma_f32_16x16x32_bf16 v[88:91], v[180:183], v[196:199], v[88:91]
	v_mfma_f32_16x16x32_bf16 v[76:79], v[172:175], v[204:207], v[76:79]
	v_mfma_f32_16x16x32_bf16 v[72:75], v[180:183], v[204:207], v[72:75]
	v_mfma_f32_16x16x32_bf16 v[68:71], v[172:175], v[212:215], v[68:71]
	v_mfma_f32_16x16x32_bf16 v[64:67], v[180:183], v[212:215], v[64:67]
	s_setprio 0
	s_barrier
	s_add_i32 s22, s47, s26
	s_mov_b32 m0, s22
	ds_read_b128 v[184:187], v150 offset:49152
	ds_read_b128 v[188:191], v150 offset:50176
	ds_read_b128 v[192:195], v150 offset:51200
	ds_read_b128 v[196:199], v150 offset:52224
	ds_read_b128 v[200:203], v150 offset:53248
	ds_read_b128 v[204:207], v150 offset:54272
	ds_read_b128 v[208:211], v150 offset:55296
	ds_read_b128 v[212:215], v150 offset:56320
	global_load_lds_dwordx4 v132, s[84:85]
	s_add_i32 m0, s22, 0x2000
	s_add_u32 s20, s20, 0x40080
	s_addc_u32 s21, s21, 0
	s_add_i32 s22, s48, s26
	global_load_lds_dwordx4 v128, s[84:85]
	s_mov_b32 m0, s22
	s_nop 0
	global_load_lds_dwordx4 v132, s[20:21]
	s_add_i32 m0, s22, 0x2000
	s_nop 0
	global_load_lds_dwordx4 v128, s[20:21]
	s_mov_b32 m0, s34
	s_nop 0
	global_load_lds_dwordx4 v134, s[86:87]
	s_mov_b32 m0, s35
	s_nop 0
	global_load_lds_dwordx4 v130, s[86:87]
	s_waitcnt vmcnt(8)
	s_waitcnt lgkmcnt(0)
	s_barrier
	s_setprio 1
	s_waitcnt lgkmcnt(0)
	v_mfma_f32_16x16x32_bf16 v[60:63], v[152:155], v[184:187], v[60:63]
	v_mfma_f32_16x16x32_bf16 v[56:59], v[160:163], v[184:187], v[56:59]
	v_mfma_f32_16x16x32_bf16 v[52:55], v[152:155], v[192:195], v[52:55]
	v_mfma_f32_16x16x32_bf16 v[48:51], v[160:163], v[192:195], v[48:51]
	v_mfma_f32_16x16x32_bf16 v[36:39], v[152:155], v[200:203], v[36:39]
	v_mfma_f32_16x16x32_bf16 v[32:35], v[160:163], v[200:203], v[32:35]
	v_mfma_f32_16x16x32_bf16 v[20:23], v[152:155], v[208:211], v[20:23]
	v_mfma_f32_16x16x32_bf16 v[16:19], v[160:163], v[208:211], v[16:19]
	v_mfma_f32_16x16x32_bf16 v[60:63], v[156:159], v[188:191], v[60:63]
	v_mfma_f32_16x16x32_bf16 v[56:59], v[164:167], v[188:191], v[56:59]
	v_mfma_f32_16x16x32_bf16 v[52:55], v[156:159], v[196:199], v[52:55]
	v_mfma_f32_16x16x32_bf16 v[48:51], v[164:167], v[196:199], v[48:51]
	v_mfma_f32_16x16x32_bf16 v[36:39], v[156:159], v[204:207], v[36:39]
	v_mfma_f32_16x16x32_bf16 v[32:35], v[164:167], v[204:207], v[32:35]
	v_mfma_f32_16x16x32_bf16 v[20:23], v[156:159], v[212:215], v[20:23]
	v_mfma_f32_16x16x32_bf16 v[16:19], v[164:167], v[212:215], v[16:19]


	v_mfma_f32_16x16x32_bf16 v[44:47], v[168:171], v[184:187], v[44:47]
	v_mfma_f32_16x16x32_bf16 v[40:43], v[176:179], v[184:187], v[40:43]
	v_mfma_f32_16x16x32_bf16 v[28:31], v[168:171], v[192:195], v[28:31]
	v_mfma_f32_16x16x32_bf16 v[24:27], v[176:179], v[192:195], v[24:27]
	v_mfma_f32_16x16x32_bf16 v[12:15], v[168:171], v[200:203], v[12:15]
	v_mfma_f32_16x16x32_bf16 v[8:11], v[176:179], v[200:203], v[8:11]
	v_mfma_f32_16x16x32_bf16 v[4:7], v[168:171], v[208:211], v[4:7]
	v_mfma_f32_16x16x32_bf16 v[0:3], v[176:179], v[208:211], v[0:3]
	v_mfma_f32_16x16x32_bf16 v[44:47], v[172:175], v[188:191], v[44:47]
	v_mfma_f32_16x16x32_bf16 v[40:43], v[180:183], v[188:191], v[40:43]
	v_mfma_f32_16x16x32_bf16 v[28:31], v[172:175], v[196:199], v[28:31]
	v_mfma_f32_16x16x32_bf16 v[24:27], v[180:183], v[196:199], v[24:27]
	v_mfma_f32_16x16x32_bf16 v[12:15], v[172:175], v[204:207], v[12:15]
	v_mfma_f32_16x16x32_bf16 v[8:11], v[180:183], v[204:207], v[8:11]
	v_mfma_f32_16x16x32_bf16 v[4:7], v[172:175], v[212:215], v[4:7]
	v_mfma_f32_16x16x32_bf16 v[0:3], v[180:183], v[212:215], v[0:3]
	s_setprio 0
	s_barrier
	s_add_i32 s46, s46, 2
	s_add_u32 s18, s18, 0x100
	s_addc_u32 s19, s19, 0
	s_add_u32 s44, s44, 0x100
	s_addc_u32 s45, s45, 0
.LBB0_131:
	ds_read_b128 v[152:155], v148
	ds_read_b128 v[156:159], v148 offset:1024
	ds_read_b128 v[160:163], v148 offset:2048
	ds_read_b128 v[164:167], v148 offset:3072
	ds_read_b128 v[168:171], v149
	ds_read_b128 v[172:175], v149 offset:1024
	ds_read_b128 v[176:179], v149 offset:2048
	ds_read_b128 v[180:183], v149 offset:3072
	s_add_u32 s20, s18, 0xfffc0080
	s_addc_u32 s21, s19, -1
	s_cmp_eq_u32 s46, 12
	s_cselect_b32 s23, s13, s21
	s_cselect_b32 s22, s42, s20
	s_cselect_b32 s21, s11, s45
	s_cselect_b32 s20, s43, s44
	s_add_i32 m0, s9, 0xc000
	ds_read_b128 v[184:187], v150
	ds_read_b128 v[188:191], v150 offset:1024
	ds_read_b128 v[192:195], v150 offset:2048
	ds_read_b128 v[196:199], v150 offset:3072
	ds_read_b128 v[200:203], v150 offset:4096
	ds_read_b128 v[204:207], v150 offset:5120
	ds_read_b128 v[208:211], v150 offset:6144
	ds_read_b128 v[212:215], v150 offset:7168
	global_load_lds_dwordx4 v136, s[18:19]
	s_add_i32 m0, s9, 0xe000
	s_nop 0
	global_load_lds_dwordx4 v138, s[18:19]
	s_waitcnt vmcnt(8)
	s_waitcnt lgkmcnt(0)
	s_barrier
	s_setprio 1
	s_waitcnt lgkmcnt(0)
	v_mfma_f32_16x16x32_bf16 v[124:127], v[152:155], v[184:187], v[124:127]
	v_mfma_f32_16x16x32_bf16 v[120:123], v[160:163], v[184:187], v[120:123]
	v_mfma_f32_16x16x32_bf16 v[116:119], v[152:155], v[192:195], v[116:119]
	v_mfma_f32_16x16x32_bf16 v[112:115], v[160:163], v[192:195], v[112:115]
	v_mfma_f32_16x16x32_bf16 v[100:103], v[152:155], v[200:203], v[100:103]
	v_mfma_f32_16x16x32_bf16 v[96:99], v[160:163], v[200:203], v[96:99]
	v_mfma_f32_16x16x32_bf16 v[84:87], v[152:155], v[208:211], v[84:87]
	v_mfma_f32_16x16x32_bf16 v[80:83], v[160:163], v[208:211], v[80:83]
	v_mfma_f32_16x16x32_bf16 v[124:127], v[156:159], v[188:191], v[124:127]
	v_mfma_f32_16x16x32_bf16 v[120:123], v[164:167], v[188:191], v[120:123]
	v_mfma_f32_16x16x32_bf16 v[116:119], v[156:159], v[196:199], v[116:119]
	v_mfma_f32_16x16x32_bf16 v[112:115], v[164:167], v[196:199], v[112:115]
	v_mfma_f32_16x16x32_bf16 v[100:103], v[156:159], v[204:207], v[100:103]
	v_mfma_f32_16x16x32_bf16 v[96:99], v[164:167], v[204:207], v[96:99]
	v_mfma_f32_16x16x32_bf16 v[84:87], v[156:159], v[212:215], v[84:87]
	v_mfma_f32_16x16x32_bf16 v[80:83], v[164:167], v[212:215], v[80:83]


	v_mfma_f32_16x16x32_bf16 v[108:111], v[168:171], v[184:187], v[108:111]
	v_mfma_f32_16x16x32_bf16 v[104:107], v[176:179], v[184:187], v[104:107]
	v_mfma_f32_16x16x32_bf16 v[92:95], v[168:171], v[192:195], v[92:95]
	v_mfma_f32_16x16x32_bf16 v[88:91], v[176:179], v[192:195], v[88:91]
	v_mfma_f32_16x16x32_bf16 v[76:79], v[168:171], v[200:203], v[76:79]
	v_mfma_f32_16x16x32_bf16 v[72:75], v[176:179], v[200:203], v[72:75]
	v_mfma_f32_16x16x32_bf16 v[68:71], v[168:171], v[208:211], v[68:71]
	v_mfma_f32_16x16x32_bf16 v[64:67], v[176:179], v[208:211], v[64:67]
	v_mfma_f32_16x16x32_bf16 v[108:111], v[172:175], v[188:191], v[108:111]
	v_mfma_f32_16x16x32_bf16 v[104:107], v[180:183], v[188:191], v[104:107]
	v_mfma_f32_16x16x32_bf16 v[92:95], v[172:175], v[196:199], v[92:95]
	v_mfma_f32_16x16x32_bf16 v[88:91], v[180:183], v[196:199], v[88:91]
	v_mfma_f32_16x16x32_bf16 v[76:79], v[172:175], v[204:207], v[76:79]
	v_mfma_f32_16x16x32_bf16 v[72:75], v[180:183], v[204:207], v[72:75]
	v_mfma_f32_16x16x32_bf16 v[68:71], v[172:175], v[212:215], v[68:71]
	v_mfma_f32_16x16x32_bf16 v[64:67], v[180:183], v[212:215], v[64:67]
	s_setprio 0
	s_barrier
	s_add_i32 s47, s38, s26
	s_mov_b32 m0, s47
	ds_read_b128 v[184:187], v150 offset:16384
	ds_read_b128 v[188:191], v150 offset:17408
	ds_read_b128 v[192:195], v150 offset:18432
	ds_read_b128 v[196:199], v150 offset:19456
	ds_read_b128 v[200:203], v150 offset:20480
	ds_read_b128 v[204:207], v150 offset:21504
	ds_read_b128 v[208:211], v150 offset:22528
	ds_read_b128 v[212:215], v150 offset:23552
	global_load_lds_dwordx4 v132, s[20:21]
	s_add_i32 m0, s47, 0x2000
	s_add_u32 s48, s20, 0x40000
	s_addc_u32 s49, s21, 0
	s_add_i32 s47, s39, s26
	global_load_lds_dwordx4 v128, s[20:21]
	s_mov_b32 m0, s47
	s_nop 0
	global_load_lds_dwordx4 v132, s[48:49]
	s_add_i32 m0, s47, 0x2000
	s_nop 0
	global_load_lds_dwordx4 v128, s[48:49]
	s_mov_b32 m0, s9
	s_nop 0
	global_load_lds_dwordx4 v134, s[22:23]
	s_mov_b32 m0, s29
	s_nop 0
	global_load_lds_dwordx4 v130, s[22:23]
	s_add_u32 s84, s20, s4
	s_addc_u32 s85, s21, s5
	s_add_u32 s86, s22, s4
	s_addc_u32 s87, s23, s5
	s_waitcnt vmcnt(8)
	s_waitcnt lgkmcnt(0)
	s_barrier
	s_setprio 1
	s_waitcnt lgkmcnt(0)
	v_mfma_f32_16x16x32_bf16 v[60:63], v[152:155], v[184:187], v[60:63]
	v_mfma_f32_16x16x32_bf16 v[56:59], v[160:163], v[184:187], v[56:59]
	v_mfma_f32_16x16x32_bf16 v[52:55], v[152:155], v[192:195], v[52:55]
	v_mfma_f32_16x16x32_bf16 v[48:51], v[160:163], v[192:195], v[48:51]
	v_mfma_f32_16x16x32_bf16 v[36:39], v[152:155], v[200:203], v[36:39]
	v_mfma_f32_16x16x32_bf16 v[32:35], v[160:163], v[200:203], v[32:35]
	v_mfma_f32_16x16x32_bf16 v[20:23], v[152:155], v[208:211], v[20:23]
	v_mfma_f32_16x16x32_bf16 v[16:19], v[160:163], v[208:211], v[16:19]
	v_mfma_f32_16x16x32_bf16 v[60:63], v[156:159], v[188:191], v[60:63]
	v_mfma_f32_16x16x32_bf16 v[56:59], v[164:167], v[188:191], v[56:59]
	v_mfma_f32_16x16x32_bf16 v[52:55], v[156:159], v[196:199], v[52:55]
	v_mfma_f32_16x16x32_bf16 v[48:51], v[164:167], v[196:199], v[48:51]
	v_mfma_f32_16x16x32_bf16 v[36:39], v[156:159], v[204:207], v[36:39]
	v_mfma_f32_16x16x32_bf16 v[32:35], v[164:167], v[204:207], v[32:35]
	v_mfma_f32_16x16x32_bf16 v[20:23], v[156:159], v[212:215], v[20:23]
	v_mfma_f32_16x16x32_bf16 v[16:19], v[164:167], v[212:215], v[16:19]


	v_mfma_f32_16x16x32_bf16 v[44:47], v[168:171], v[184:187], v[44:47]
	v_mfma_f32_16x16x32_bf16 v[40:43], v[176:179], v[184:187], v[40:43]
	v_mfma_f32_16x16x32_bf16 v[28:31], v[168:171], v[192:195], v[28:31]
	v_mfma_f32_16x16x32_bf16 v[24:27], v[176:179], v[192:195], v[24:27]
	v_mfma_f32_16x16x32_bf16 v[12:15], v[168:171], v[200:203], v[12:15]
	v_mfma_f32_16x16x32_bf16 v[8:11], v[176:179], v[200:203], v[8:11]
	v_mfma_f32_16x16x32_bf16 v[4:7], v[168:171], v[208:211], v[4:7]
	v_mfma_f32_16x16x32_bf16 v[0:3], v[176:179], v[208:211], v[0:3]
	v_mfma_f32_16x16x32_bf16 v[44:47], v[172:175], v[188:191], v[44:47]
	v_mfma_f32_16x16x32_bf16 v[40:43], v[180:183], v[188:191], v[40:43]
	v_mfma_f32_16x16x32_bf16 v[28:31], v[172:175], v[196:199], v[28:31]
	v_mfma_f32_16x16x32_bf16 v[24:27], v[180:183], v[196:199], v[24:27]
	v_mfma_f32_16x16x32_bf16 v[12:15], v[172:175], v[204:207], v[12:15]
	v_mfma_f32_16x16x32_bf16 v[8:11], v[180:183], v[204:207], v[8:11]
	v_mfma_f32_16x16x32_bf16 v[4:7], v[172:175], v[212:215], v[4:7]
	v_mfma_f32_16x16x32_bf16 v[0:3], v[180:183], v[212:215], v[0:3]
	s_setprio 0
	s_barrier
	s_add_i32 s47, 0, 0x18000
	v_add_u32_e32 v151, s47, v146
	s_add_i32 s48, 0, 0x1c000
	ds_read_b128 v[152:155], v151
	ds_read_b128 v[156:159], v151 offset:1024
	ds_read_b128 v[160:163], v151 offset:2048
	ds_read_b128 v[164:167], v151 offset:3072
	v_add_u32_e32 v151, s48, v146
	ds_read_b128 v[168:171], v151
	ds_read_b128 v[172:175], v151 offset:1024
	ds_read_b128 v[176:179], v151 offset:2048
	ds_read_b128 v[180:183], v151 offset:3072
	s_add_u32 s22, s22, 0x40000
	s_addc_u32 s23, s23, 0
	s_mov_b32 m0, s30
	ds_read_b128 v[184:187], v150 offset:32768
	ds_read_b128 v[188:191], v150 offset:33792
	ds_read_b128 v[192:195], v150 offset:34816
	ds_read_b128 v[196:199], v150 offset:35840
	ds_read_b128 v[200:203], v150 offset:36864
	ds_read_b128 v[204:207], v150 offset:37888
	ds_read_b128 v[208:211], v150 offset:38912
	ds_read_b128 v[212:215], v150 offset:39936
	global_load_lds_dwordx4 v134, s[22:23]
	s_mov_b32 m0, s31
	s_nop 0
	global_load_lds_dwordx4 v130, s[22:23]
	s_waitcnt vmcnt(8)
	s_waitcnt lgkmcnt(0)
	s_barrier
	s_setprio 1
	s_waitcnt lgkmcnt(0)
	v_mfma_f32_16x16x32_bf16 v[124:127], v[152:155], v[184:187], v[124:127]
	v_mfma_f32_16x16x32_bf16 v[120:123], v[160:163], v[184:187], v[120:123]
	v_mfma_f32_16x16x32_bf16 v[116:119], v[152:155], v[192:195], v[116:119]
	v_mfma_f32_16x16x32_bf16 v[112:115], v[160:163], v[192:195], v[112:115]
	v_mfma_f32_16x16x32_bf16 v[100:103], v[152:155], v[200:203], v[100:103]
	v_mfma_f32_16x16x32_bf16 v[96:99], v[160:163], v[200:203], v[96:99]
	v_mfma_f32_16x16x32_bf16 v[84:87], v[152:155], v[208:211], v[84:87]
	v_mfma_f32_16x16x32_bf16 v[80:83], v[160:163], v[208:211], v[80:83]
	v_mfma_f32_16x16x32_bf16 v[124:127], v[156:159], v[188:191], v[124:127]
	v_mfma_f32_16x16x32_bf16 v[120:123], v[164:167], v[188:191], v[120:123]
	v_mfma_f32_16x16x32_bf16 v[116:119], v[156:159], v[196:199], v[116:119]
	v_mfma_f32_16x16x32_bf16 v[112:115], v[164:167], v[196:199], v[112:115]
	v_mfma_f32_16x16x32_bf16 v[100:103], v[156:159], v[204:207], v[100:103]
	v_mfma_f32_16x16x32_bf16 v[96:99], v[164:167], v[204:207], v[96:99]
	v_mfma_f32_16x16x32_bf16 v[84:87], v[156:159], v[212:215], v[84:87]
	v_mfma_f32_16x16x32_bf16 v[80:83], v[164:167], v[212:215], v[80:83]


	v_mfma_f32_16x16x32_bf16 v[108:111], v[168:171], v[184:187], v[108:111]
	v_mfma_f32_16x16x32_bf16 v[104:107], v[176:179], v[184:187], v[104:107]
	v_mfma_f32_16x16x32_bf16 v[92:95], v[168:171], v[192:195], v[92:95]
	v_mfma_f32_16x16x32_bf16 v[88:91], v[176:179], v[192:195], v[88:91]
	v_mfma_f32_16x16x32_bf16 v[76:79], v[168:171], v[200:203], v[76:79]
	v_mfma_f32_16x16x32_bf16 v[72:75], v[176:179], v[200:203], v[72:75]
	v_mfma_f32_16x16x32_bf16 v[68:71], v[168:171], v[208:211], v[68:71]
	v_mfma_f32_16x16x32_bf16 v[64:67], v[176:179], v[208:211], v[64:67]
	v_mfma_f32_16x16x32_bf16 v[108:111], v[172:175], v[188:191], v[108:111]
	v_mfma_f32_16x16x32_bf16 v[104:107], v[180:183], v[188:191], v[104:107]
	v_mfma_f32_16x16x32_bf16 v[92:95], v[172:175], v[196:199], v[92:95]
	v_mfma_f32_16x16x32_bf16 v[88:91], v[180:183], v[196:199], v[88:91]
	v_mfma_f32_16x16x32_bf16 v[76:79], v[172:175], v[204:207], v[76:79]
	v_mfma_f32_16x16x32_bf16 v[72:75], v[180:183], v[204:207], v[72:75]
	v_mfma_f32_16x16x32_bf16 v[68:71], v[172:175], v[212:215], v[68:71]
	v_mfma_f32_16x16x32_bf16 v[64:67], v[180:183], v[212:215], v[64:67]
	s_setprio 0
	s_barrier
	s_add_i32 s22, s47, s26
	s_mov_b32 m0, s22
	ds_read_b128 v[184:187], v150 offset:49152
	ds_read_b128 v[188:191], v150 offset:50176
	ds_read_b128 v[192:195], v150 offset:51200
	ds_read_b128 v[196:199], v150 offset:52224
	ds_read_b128 v[200:203], v150 offset:53248
	ds_read_b128 v[204:207], v150 offset:54272
	ds_read_b128 v[208:211], v150 offset:55296
	ds_read_b128 v[212:215], v150 offset:56320
	global_load_lds_dwordx4 v132, s[84:85]
	s_add_i32 m0, s22, 0x2000
	s_add_u32 s20, s20, 0x40080
	s_addc_u32 s21, s21, 0
	s_add_i32 s22, s48, s26
	global_load_lds_dwordx4 v128, s[84:85]
	s_mov_b32 m0, s22
	s_nop 0
	global_load_lds_dwordx4 v132, s[20:21]
	s_add_i32 m0, s22, 0x2000
	s_nop 0
	global_load_lds_dwordx4 v128, s[20:21]
	s_mov_b32 m0, s34
	s_nop 0
	global_load_lds_dwordx4 v134, s[86:87]
	s_mov_b32 m0, s35
	s_nop 0
	global_load_lds_dwordx4 v130, s[86:87]
	s_waitcnt vmcnt(8)
	s_waitcnt lgkmcnt(0)
	s_barrier
	s_setprio 1
	s_waitcnt lgkmcnt(0)
	v_mfma_f32_16x16x32_bf16 v[60:63], v[152:155], v[184:187], v[60:63]
	v_mfma_f32_16x16x32_bf16 v[56:59], v[160:163], v[184:187], v[56:59]
	v_mfma_f32_16x16x32_bf16 v[52:55], v[152:155], v[192:195], v[52:55]
	v_mfma_f32_16x16x32_bf16 v[48:51], v[160:163], v[192:195], v[48:51]
	v_mfma_f32_16x16x32_bf16 v[36:39], v[152:155], v[200:203], v[36:39]
	v_mfma_f32_16x16x32_bf16 v[32:35], v[160:163], v[200:203], v[32:35]
	v_mfma_f32_16x16x32_bf16 v[20:23], v[152:155], v[208:211], v[20:23]
	v_mfma_f32_16x16x32_bf16 v[16:19], v[160:163], v[208:211], v[16:19]
	v_mfma_f32_16x16x32_bf16 v[60:63], v[156:159], v[188:191], v[60:63]
	v_mfma_f32_16x16x32_bf16 v[56:59], v[164:167], v[188:191], v[56:59]
	v_mfma_f32_16x16x32_bf16 v[52:55], v[156:159], v[196:199], v[52:55]
	v_mfma_f32_16x16x32_bf16 v[48:51], v[164:167], v[196:199], v[48:51]
	v_mfma_f32_16x16x32_bf16 v[36:39], v[156:159], v[204:207], v[36:39]
	v_mfma_f32_16x16x32_bf16 v[32:35], v[164:167], v[204:207], v[32:35]
	v_mfma_f32_16x16x32_bf16 v[20:23], v[156:159], v[212:215], v[20:23]
	v_mfma_f32_16x16x32_bf16 v[16:19], v[164:167], v[212:215], v[16:19]


	v_mfma_f32_16x16x32_bf16 v[44:47], v[168:171], v[184:187], v[44:47]
	v_mfma_f32_16x16x32_bf16 v[40:43], v[176:179], v[184:187], v[40:43]
	v_mfma_f32_16x16x32_bf16 v[28:31], v[168:171], v[192:195], v[28:31]
	v_mfma_f32_16x16x32_bf16 v[24:27], v[176:179], v[192:195], v[24:27]
	v_mfma_f32_16x16x32_bf16 v[12:15], v[168:171], v[200:203], v[12:15]
	v_mfma_f32_16x16x32_bf16 v[8:11], v[176:179], v[200:203], v[8:11]
	v_mfma_f32_16x16x32_bf16 v[4:7], v[168:171], v[208:211], v[4:7]
	v_mfma_f32_16x16x32_bf16 v[0:3], v[176:179], v[208:211], v[0:3]
	v_mfma_f32_16x16x32_bf16 v[44:47], v[172:175], v[188:191], v[44:47]
	v_mfma_f32_16x16x32_bf16 v[40:43], v[180:183], v[188:191], v[40:43]
	v_mfma_f32_16x16x32_bf16 v[28:31], v[172:175], v[196:199], v[28:31]
	v_mfma_f32_16x16x32_bf16 v[24:27], v[180:183], v[196:199], v[24:27]
	v_mfma_f32_16x16x32_bf16 v[12:15], v[172:175], v[204:207], v[12:15]
	v_mfma_f32_16x16x32_bf16 v[8:11], v[180:183], v[204:207], v[8:11]
	v_mfma_f32_16x16x32_bf16 v[4:7], v[172:175], v[212:215], v[4:7]
	v_mfma_f32_16x16x32_bf16 v[0:3], v[180:183], v[212:215], v[0:3]
	s_setprio 0
	s_barrier
	s_add_i32 s46, s46, 2
	s_add_u32 s18, s18, 0x100
	s_addc_u32 s19, s19, 0
	s_add_u32 s44, s44, 0x100
	s_addc_u32 s45, s45, 0
	s_cmp_gt_u32 s46, 13
	s_cbranch_scc0 .LBB0_131
	s_and_b64 vcc, exec, s[6:7]
	s_cbranch_vccz .LBB0_134
	s_barrier

.LBB0_365:
	s_add_u32 s10, s60, s8
	s_addc_u32 s11, s61, s9
	s_add_u32 s10, s10, 0x5dc0100
	s_addc_u32 s11, s11, 0
	s_add_u32 s65, s62, s8
	s_addc_u32 s66, s63, s9
	s_add_i32 s67, 0, 0x10000
	s_cmpk_eq_i32 s8, 0x700
	s_cselect_b32 s27, s7, s11
	s_cselect_b32 s26, s6, s10
	s_cselect_b32 s11, s1, s66
	s_cselect_b32 s10, s0, s65
	s_add_i32 s65, 0, 0x14000
	v_add_u32_e32 v144, s67, v122
	v_add_u32_e32 v165, s65, v122
	ds_read_b128 v[124:127], v144
	ds_read_b128 v[128:131], v144 offset:1024
	ds_read_b128 v[132:135], v144 offset:2048
	ds_read_b128 v[144:147], v144 offset:3072
	ds_read_b128 v[148:151], v165
	ds_read_b128 v[160:163], v165 offset:1024
	ds_read_b128 v[166:169], v165 offset:2048
	ds_read_b128 v[170:173], v165 offset:3072
	v_lshl_add_u64 v[206:207], v[110:111], 0, s[8:9]
	s_add_i32 m0, s23, 0xc000
	ds_read_b128 v[174:177], v123
	ds_read_b128 v[178:181], v123 offset:1024
	ds_read_b128 v[182:185], v123 offset:2048
	ds_read_b128 v[186:189], v123 offset:3072
	ds_read_b128 v[190:193], v123 offset:4096
	ds_read_b128 v[194:197], v123 offset:5120
	ds_read_b128 v[198:201], v123 offset:6144
	ds_read_b128 v[202:205], v123 offset:7168
	global_load_lds_dwordx4 v[206:207], off
	v_lshl_add_u64 v[206:207], v[120:121], 0, s[8:9]
	s_add_i32 m0, s23, 0xe000
	s_nop 0
	global_load_lds_dwordx4 v[206:207], off
	s_waitcnt vmcnt(8)
	s_waitcnt lgkmcnt(0)
	s_barrier
	s_setprio 1
	s_waitcnt lgkmcnt(0)
	v_mfma_f32_16x16x32_bf16 v[156:159], v[124:127], v[174:177], v[156:159]
	v_mfma_f32_16x16x32_bf16 v[152:155], v[132:135], v[174:177], v[152:155]
	v_mfma_f32_16x16x32_bf16 v[116:119], v[124:127], v[182:185], v[116:119]
	v_mfma_f32_16x16x32_bf16 v[112:115], v[132:135], v[182:185], v[112:115]
	v_mfma_f32_16x16x32_bf16 v[92:95], v[124:127], v[190:193], v[92:95]
	v_mfma_f32_16x16x32_bf16 v[88:91], v[132:135], v[190:193], v[88:91]
	v_mfma_f32_16x16x32_bf16 v[76:79], v[124:127], v[198:201], v[76:79]
	v_mfma_f32_16x16x32_bf16 v[72:75], v[132:135], v[198:201], v[72:75]
	v_mfma_f32_16x16x32_bf16 v[156:159], v[128:131], v[178:181], v[156:159]
	v_mfma_f32_16x16x32_bf16 v[152:155], v[144:147], v[178:181], v[152:155]
	v_mfma_f32_16x16x32_bf16 v[116:119], v[128:131], v[186:189], v[116:119]
	v_mfma_f32_16x16x32_bf16 v[112:115], v[144:147], v[186:189], v[112:115]
	v_mfma_f32_16x16x32_bf16 v[92:95], v[128:131], v[194:197], v[92:95]
	v_mfma_f32_16x16x32_bf16 v[88:91], v[144:147], v[194:197], v[88:91]
	v_mfma_f32_16x16x32_bf16 v[76:79], v[128:131], v[202:205], v[76:79]
	v_mfma_f32_16x16x32_bf16 v[72:75], v[144:147], v[202:205], v[72:75]


	v_mfma_f32_16x16x32_bf16 v[140:143], v[148:151], v[174:177], v[140:143]
	v_mfma_f32_16x16x32_bf16 v[136:139], v[166:169], v[174:177], v[136:139]
	v_mfma_f32_16x16x32_bf16 v[104:107], v[148:151], v[182:185], v[104:107]
	v_mfma_f32_16x16x32_bf16 v[96:99], v[166:169], v[182:185], v[96:99]
	v_mfma_f32_16x16x32_bf16 v[84:87], v[148:151], v[190:193], v[84:87]
	v_mfma_f32_16x16x32_bf16 v[80:83], v[166:169], v[190:193], v[80:83]
	v_mfma_f32_16x16x32_bf16 v[68:71], v[148:151], v[198:201], v[68:71]
	v_mfma_f32_16x16x32_bf16 v[64:67], v[166:169], v[198:201], v[64:67]
	v_mfma_f32_16x16x32_bf16 v[140:143], v[160:163], v[178:181], v[140:143]
	v_mfma_f32_16x16x32_bf16 v[136:139], v[170:173], v[178:181], v[136:139]
	v_mfma_f32_16x16x32_bf16 v[104:107], v[160:163], v[186:189], v[104:107]
	v_mfma_f32_16x16x32_bf16 v[96:99], v[170:173], v[186:189], v[96:99]
	v_mfma_f32_16x16x32_bf16 v[84:87], v[160:163], v[194:197], v[84:87]
	v_mfma_f32_16x16x32_bf16 v[80:83], v[170:173], v[194:197], v[80:83]
	v_mfma_f32_16x16x32_bf16 v[68:71], v[160:163], v[202:205], v[68:71]
	v_mfma_f32_16x16x32_bf16 v[64:67], v[170:173], v[202:205], v[64:67]
	s_setprio 0
	s_barrier
	s_add_i32 s66, s67, s48
	s_mov_b32 m0, s66
	ds_read_b128 v[174:177], v123 offset:16384
	ds_read_b128 v[178:181], v123 offset:17408
	ds_read_b128 v[182:185], v123 offset:18432
	ds_read_b128 v[186:189], v123 offset:19456
	ds_read_b128 v[190:193], v123 offset:20480
	ds_read_b128 v[194:197], v123 offset:21504
	ds_read_b128 v[198:201], v123 offset:22528
	ds_read_b128 v[202:205], v123 offset:23552
	global_load_lds_dwordx4 v212, s[10:11]
	s_add_i32 m0, s66, 0x2000
	s_add_u32 s66, s10, 0x40000
	s_addc_u32 s67, s11, 0
	s_add_i32 s65, s65, s48
	global_load_lds_dwordx4 v100, s[10:11]
	s_mov_b32 m0, s65
	s_nop 0
	global_load_lds_dwordx4 v212, s[66:67]
	s_add_i32 m0, s65, 0x2000
	s_nop 0
	global_load_lds_dwordx4 v100, s[66:67]
	s_mov_b32 m0, s23
	s_nop 0
	global_load_lds_dwordx4 v108, s[26:27]
	s_mov_b32 m0, s49
	s_nop 0
	global_load_lds_dwordx4 v102, s[26:27]
	s_add_u32 s86, s26, s34
	s_addc_u32 s87, s27, s35
	s_add_u32 s84, s10, s34
	s_addc_u32 s85, s11, s35
	s_waitcnt vmcnt(8)
	s_waitcnt lgkmcnt(0)
	s_barrier
	s_setprio 1
	s_waitcnt lgkmcnt(0)
	v_mfma_f32_16x16x32_bf16 v[60:63], v[124:127], v[174:177], v[60:63]
	v_mfma_f32_16x16x32_bf16 v[56:59], v[132:135], v[174:177], v[56:59]
	v_mfma_f32_16x16x32_bf16 v[44:47], v[124:127], v[182:185], v[44:47]
	v_mfma_f32_16x16x32_bf16 v[40:43], v[132:135], v[182:185], v[40:43]
	v_mfma_f32_16x16x32_bf16 v[28:31], v[124:127], v[190:193], v[28:31]
	v_mfma_f32_16x16x32_bf16 v[24:27], v[132:135], v[190:193], v[24:27]
	v_mfma_f32_16x16x32_bf16 v[12:15], v[124:127], v[198:201], v[12:15]
	v_mfma_f32_16x16x32_bf16 v[8:11], v[132:135], v[198:201], v[8:11]
	v_mfma_f32_16x16x32_bf16 v[60:63], v[128:131], v[178:181], v[60:63]
	v_mfma_f32_16x16x32_bf16 v[56:59], v[144:147], v[178:181], v[56:59]
	v_mfma_f32_16x16x32_bf16 v[44:47], v[128:131], v[186:189], v[44:47]
	v_mfma_f32_16x16x32_bf16 v[40:43], v[144:147], v[186:189], v[40:43]
	v_mfma_f32_16x16x32_bf16 v[28:31], v[128:131], v[194:197], v[28:31]
	v_mfma_f32_16x16x32_bf16 v[24:27], v[144:147], v[194:197], v[24:27]
	v_mfma_f32_16x16x32_bf16 v[12:15], v[128:131], v[202:205], v[12:15]
	v_mfma_f32_16x16x32_bf16 v[8:11], v[144:147], v[202:205], v[8:11]


	v_mfma_f32_16x16x32_bf16 v[52:55], v[148:151], v[174:177], v[52:55]
	v_mfma_f32_16x16x32_bf16 v[48:51], v[166:169], v[174:177], v[48:51]
	v_mfma_f32_16x16x32_bf16 v[36:39], v[148:151], v[182:185], v[36:39]
	v_mfma_f32_16x16x32_bf16 v[32:35], v[166:169], v[182:185], v[32:35]
	v_mfma_f32_16x16x32_bf16 v[20:23], v[148:151], v[190:193], v[20:23]
	v_mfma_f32_16x16x32_bf16 v[16:19], v[166:169], v[190:193], v[16:19]
	v_mfma_f32_16x16x32_bf16 v[4:7], v[148:151], v[198:201], v[4:7]
	v_mfma_f32_16x16x32_bf16 v[0:3], v[166:169], v[198:201], v[0:3]
	v_mfma_f32_16x16x32_bf16 v[52:55], v[160:163], v[178:181], v[52:55]
	v_mfma_f32_16x16x32_bf16 v[48:51], v[170:173], v[178:181], v[48:51]
	v_mfma_f32_16x16x32_bf16 v[36:39], v[160:163], v[186:189], v[36:39]
	v_mfma_f32_16x16x32_bf16 v[32:35], v[170:173], v[186:189], v[32:35]
	v_mfma_f32_16x16x32_bf16 v[20:23], v[160:163], v[194:197], v[20:23]
	v_mfma_f32_16x16x32_bf16 v[16:19], v[170:173], v[194:197], v[16:19]
	v_mfma_f32_16x16x32_bf16 v[4:7], v[160:163], v[202:205], v[4:7]
	v_mfma_f32_16x16x32_bf16 v[0:3], v[170:173], v[202:205], v[0:3]
	s_setprio 0
	s_barrier
	s_add_i32 s65, 0, 0x18000
	s_add_i32 s66, 0, 0x1c000
	v_add_u32_e32 v144, s65, v122
	v_add_u32_e32 v165, s66, v122
	ds_read_b128 v[124:127], v144
	ds_read_b128 v[128:131], v144 offset:1024
	ds_read_b128 v[132:135], v144 offset:2048
	ds_read_b128 v[144:147], v144 offset:3072
	ds_read_b128 v[148:151], v165
	ds_read_b128 v[160:163], v165 offset:1024
	ds_read_b128 v[166:169], v165 offset:2048
	ds_read_b128 v[170:173], v165 offset:3072
	s_add_u32 s26, s26, 0x40000
	s_addc_u32 s27, s27, 0
	s_mov_b32 m0, s50
	ds_read_b128 v[174:177], v123 offset:32768
	ds_read_b128 v[178:181], v123 offset:33792
	ds_read_b128 v[182:185], v123 offset:34816
	ds_read_b128 v[186:189], v123 offset:35840
	ds_read_b128 v[190:193], v123 offset:36864
	ds_read_b128 v[194:197], v123 offset:37888
	ds_read_b128 v[198:201], v123 offset:38912
	ds_read_b128 v[202:205], v123 offset:39936
	global_load_lds_dwordx4 v108, s[26:27]
	s_mov_b32 m0, s51
	s_nop 0
	global_load_lds_dwordx4 v102, s[26:27]
	s_waitcnt vmcnt(8)
	s_waitcnt lgkmcnt(0)
	s_barrier
	s_setprio 1
	s_waitcnt lgkmcnt(0)
	v_mfma_f32_16x16x32_bf16 v[156:159], v[124:127], v[174:177], v[156:159]
	v_mfma_f32_16x16x32_bf16 v[152:155], v[132:135], v[174:177], v[152:155]
	v_mfma_f32_16x16x32_bf16 v[116:119], v[124:127], v[182:185], v[116:119]
	v_mfma_f32_16x16x32_bf16 v[112:115], v[132:135], v[182:185], v[112:115]
	v_mfma_f32_16x16x32_bf16 v[92:95], v[124:127], v[190:193], v[92:95]
	v_mfma_f32_16x16x32_bf16 v[88:91], v[132:135], v[190:193], v[88:91]
	v_mfma_f32_16x16x32_bf16 v[76:79], v[124:127], v[198:201], v[76:79]
	v_mfma_f32_16x16x32_bf16 v[72:75], v[132:135], v[198:201], v[72:75]
	v_mfma_f32_16x16x32_bf16 v[156:159], v[128:131], v[178:181], v[156:159]
	v_mfma_f32_16x16x32_bf16 v[152:155], v[144:147], v[178:181], v[152:155]
	v_mfma_f32_16x16x32_bf16 v[116:119], v[128:131], v[186:189], v[116:119]
	v_mfma_f32_16x16x32_bf16 v[112:115], v[144:147], v[186:189], v[112:115]
	v_mfma_f32_16x16x32_bf16 v[92:95], v[128:131], v[194:197], v[92:95]
	v_mfma_f32_16x16x32_bf16 v[88:91], v[144:147], v[194:197], v[88:91]
	v_mfma_f32_16x16x32_bf16 v[76:79], v[128:131], v[202:205], v[76:79]
	v_mfma_f32_16x16x32_bf16 v[72:75], v[144:147], v[202:205], v[72:75]


	v_mfma_f32_16x16x32_bf16 v[140:143], v[148:151], v[174:177], v[140:143]
	v_mfma_f32_16x16x32_bf16 v[136:139], v[166:169], v[174:177], v[136:139]
	v_mfma_f32_16x16x32_bf16 v[104:107], v[148:151], v[182:185], v[104:107]
	v_mfma_f32_16x16x32_bf16 v[96:99], v[166:169], v[182:185], v[96:99]
	v_mfma_f32_16x16x32_bf16 v[84:87], v[148:151], v[190:193], v[84:87]
	v_mfma_f32_16x16x32_bf16 v[80:83], v[166:169], v[190:193], v[80:83]
	v_mfma_f32_16x16x32_bf16 v[68:71], v[148:151], v[198:201], v[68:71]
	v_mfma_f32_16x16x32_bf16 v[64:67], v[166:169], v[198:201], v[64:67]
	v_mfma_f32_16x16x32_bf16 v[140:143], v[160:163], v[178:181], v[140:143]
	v_mfma_f32_16x16x32_bf16 v[136:139], v[170:173], v[178:181], v[136:139]
	v_mfma_f32_16x16x32_bf16 v[104:107], v[160:163], v[186:189], v[104:107]
	v_mfma_f32_16x16x32_bf16 v[96:99], v[170:173], v[186:189], v[96:99]
	v_mfma_f32_16x16x32_bf16 v[84:87], v[160:163], v[194:197], v[84:87]
	v_mfma_f32_16x16x32_bf16 v[80:83], v[170:173], v[194:197], v[80:83]
	v_mfma_f32_16x16x32_bf16 v[68:71], v[160:163], v[202:205], v[68:71]
	v_mfma_f32_16x16x32_bf16 v[64:67], v[170:173], v[202:205], v[64:67]
	s_setprio 0
	s_barrier
	s_add_i32 s26, s65, s48
	s_mov_b32 m0, s26
	ds_read_b128 v[174:177], v123 offset:49152
	ds_read_b128 v[178:181], v123 offset:50176
	ds_read_b128 v[182:185], v123 offset:51200
	ds_read_b128 v[186:189], v123 offset:52224
	ds_read_b128 v[190:193], v123 offset:53248
	ds_read_b128 v[194:197], v123 offset:54272
	ds_read_b128 v[198:201], v123 offset:55296
	ds_read_b128 v[202:205], v123 offset:56320
	global_load_lds_dwordx4 v212, s[84:85]
	s_add_i32 m0, s26, 0x2000
	s_add_u32 s10, s10, 0x40080
	s_addc_u32 s11, s11, 0
	s_add_i32 s26, s66, s48
	global_load_lds_dwordx4 v100, s[84:85]
	s_mov_b32 m0, s26
	s_nop 0
	global_load_lds_dwordx4 v212, s[10:11]
	s_add_i32 m0, s26, 0x2000
	s_nop 0
	global_load_lds_dwordx4 v100, s[10:11]
	s_mov_b32 m0, s58
	s_nop 0
	global_load_lds_dwordx4 v108, s[86:87]
	s_mov_b32 m0, s59
	s_nop 0
	global_load_lds_dwordx4 v102, s[86:87]
	s_waitcnt vmcnt(8)
	s_waitcnt lgkmcnt(0)
	s_barrier
	s_setprio 1
	s_waitcnt lgkmcnt(0)
	v_mfma_f32_16x16x32_bf16 v[60:63], v[124:127], v[174:177], v[60:63]
	v_mfma_f32_16x16x32_bf16 v[56:59], v[132:135], v[174:177], v[56:59]
	v_mfma_f32_16x16x32_bf16 v[44:47], v[124:127], v[182:185], v[44:47]
	v_mfma_f32_16x16x32_bf16 v[40:43], v[132:135], v[182:185], v[40:43]
	v_mfma_f32_16x16x32_bf16 v[28:31], v[124:127], v[190:193], v[28:31]
	v_mfma_f32_16x16x32_bf16 v[24:27], v[132:135], v[190:193], v[24:27]
	v_mfma_f32_16x16x32_bf16 v[12:15], v[124:127], v[198:201], v[12:15]
	v_mfma_f32_16x16x32_bf16 v[8:11], v[132:135], v[198:201], v[8:11]
	v_mfma_f32_16x16x32_bf16 v[60:63], v[128:131], v[178:181], v[60:63]
	v_mfma_f32_16x16x32_bf16 v[56:59], v[144:147], v[178:181], v[56:59]
	v_mfma_f32_16x16x32_bf16 v[44:47], v[128:131], v[186:189], v[44:47]
	v_mfma_f32_16x16x32_bf16 v[40:43], v[144:147], v[186:189], v[40:43]
	v_mfma_f32_16x16x32_bf16 v[28:31], v[128:131], v[194:197], v[28:31]
	v_mfma_f32_16x16x32_bf16 v[24:27], v[144:147], v[194:197], v[24:27]
	v_mfma_f32_16x16x32_bf16 v[12:15], v[128:131], v[202:205], v[12:15]
	v_mfma_f32_16x16x32_bf16 v[8:11], v[144:147], v[202:205], v[8:11]


	v_mfma_f32_16x16x32_bf16 v[52:55], v[148:151], v[174:177], v[52:55]
	v_mfma_f32_16x16x32_bf16 v[48:51], v[166:169], v[174:177], v[48:51]
	v_mfma_f32_16x16x32_bf16 v[36:39], v[148:151], v[182:185], v[36:39]
	v_mfma_f32_16x16x32_bf16 v[32:35], v[166:169], v[182:185], v[32:35]
	v_mfma_f32_16x16x32_bf16 v[20:23], v[148:151], v[190:193], v[20:23]
	v_mfma_f32_16x16x32_bf16 v[16:19], v[166:169], v[190:193], v[16:19]
	v_mfma_f32_16x16x32_bf16 v[4:7], v[148:151], v[198:201], v[4:7]
	v_mfma_f32_16x16x32_bf16 v[0:3], v[166:169], v[198:201], v[0:3]
	v_mfma_f32_16x16x32_bf16 v[52:55], v[160:163], v[178:181], v[52:55]
	v_mfma_f32_16x16x32_bf16 v[48:51], v[170:173], v[178:181], v[48:51]
	v_mfma_f32_16x16x32_bf16 v[36:39], v[160:163], v[186:189], v[36:39]
	v_mfma_f32_16x16x32_bf16 v[32:35], v[170:173], v[186:189], v[32:35]
	v_mfma_f32_16x16x32_bf16 v[20:23], v[160:163], v[194:197], v[20:23]
	v_mfma_f32_16x16x32_bf16 v[16:19], v[170:173], v[194:197], v[16:19]
	v_mfma_f32_16x16x32_bf16 v[4:7], v[160:163], v[202:205], v[4:7]
	v_mfma_f32_16x16x32_bf16 v[0:3], v[170:173], v[202:205], v[0:3]
	s_setprio 0
	s_barrier
	s_add_i32 s64, s64, 2
	s_add_u32 s8, s8, 0x100
	s_addc_u32 s9, s9, 0
	s_cmp_lt_u32 s64, 14
	s_cbranch_scc1 .LBB0_365
	s_waitcnt vmcnt(0)
	s_cmpk_gt_u32 s47, 0xff
	s_cbranch_scc1 .LBB0_368
	s_barrier

.LBB0_497:
	s_ashr_i32 s11, s10, 31
	s_lshl_b64 s[22:23], s[10:11], 19
	s_add_u32 s22, s16, s22
	s_addc_u32 s23, s17, s23
	s_and_b64 s[24:25], s[0:1], exec
	s_cselect_b32 s11, s23, s31
	s_cselect_b32 s49, s22, s30
	s_ashr_i32 s9, s8, 31
	s_lshl_b64 s[24:25], s[8:9], 19
	s_add_u32 s24, s33, s24
	s_addc_u32 s25, s34, s25
	s_and_b64 s[50:51], s[0:1], exec
	s_cselect_b32 s9, s25, s29
	s_cselect_b32 s50, s24, s28
	v_lshl_add_u32 v152, s26, 8, v164
	s_add_u32 s26, s30, 0x40080
	v_add_u32_e32 v150, 0x80, v152
	v_add_u32_e32 v148, 0x90, v152
	v_add_u32_e32 v146, 0xa0, v152
	v_add_u32_e32 v144, 0xb0, v152
	s_addc_u32 s27, s31, 0
	v_ashrrev_i32_e32 v153, 31, v152
	v_ashrrev_i32_e32 v151, 31, v150
	v_ashrrev_i32_e32 v149, 31, v148
	v_ashrrev_i32_e32 v147, 31, v146
	v_ashrrev_i32_e32 v145, 31, v144
	s_add_u32 s51, s28, 0x100
	v_lshl_add_u64 v[154:155], v[152:153], 2, s[20:21]
	v_lshl_add_u64 v[156:157], v[150:151], 2, s[20:21]
	v_lshl_add_u64 v[158:159], v[148:149], 2, s[20:21]
	v_lshl_add_u64 v[160:161], v[146:147], 2, s[20:21]
	v_lshl_add_u64 v[162:163], v[144:145], 2, s[20:21]
	s_addc_u32 s52, s29, 0
	s_mov_b32 s53, -2
	s_mov_b64 s[28:29], 0
	v_add_u32_e32 v188, s46, v165
	v_add_u32_e32 v204, s47, v165
	ds_read_b128 v[176:179], v188
	ds_read_b128 v[180:183], v188 offset:1024
	ds_read_b128 v[184:187], v188 offset:2048
	ds_read_b128 v[188:191], v188 offset:3072
	ds_read_b128 v[192:195], v204
	ds_read_b128 v[196:199], v204 offset:1024
	ds_read_b128 v[200:203], v204 offset:2048
	ds_read_b128 v[204:207], v204 offset:3072
	s_add_u32 s30, s26, 0xfffc0080
	s_addc_u32 s31, s27, -1
	s_and_b64 s[28:29], s[28:29], exec
	s_cselect_b32 s31, s11, s31
	s_cselect_b32 s30, s49, s30
	s_cselect_b32 s29, s9, s52
	s_cselect_b32 s28, s50, s51
	s_add_i32 m0, s36, 0xc000
	ds_read_b128 v[208:211], v167
	ds_read_b128 v[212:215], v167 offset:1024
	ds_read_b128 v[216:219], v167 offset:2048
	ds_read_b128 v[220:223], v167 offset:3072
	ds_read_b128 v[224:227], v167 offset:4096
	ds_read_b128 v[230:233], v167 offset:5120
	ds_read_b128 v[234:237], v167 offset:6144
	ds_read_b128 v[238:241], v167 offset:7168
	global_load_lds_dwordx4 v136, s[26:27]
	s_add_i32 m0, s36, 0xe000
	s_nop 0
	global_load_lds_dwordx4 v138, s[26:27]
	s_waitcnt vmcnt(8)
	s_waitcnt lgkmcnt(0)
	s_barrier
	s_setprio 1
	s_waitcnt lgkmcnt(0)
	v_mfma_f32_16x16x32_bf16 v[124:127], v[176:179], v[208:211], 0
	v_mfma_f32_16x16x32_bf16 v[120:123], v[184:187], v[208:211], 0
	v_mfma_f32_16x16x32_bf16 v[108:111], v[176:179], v[216:219], 0
	v_mfma_f32_16x16x32_bf16 v[104:107], v[184:187], v[216:219], 0
	v_mfma_f32_16x16x32_bf16 v[92:95], v[176:179], v[224:227], 0
	v_mfma_f32_16x16x32_bf16 v[88:91], v[184:187], v[224:227], 0
	v_mfma_f32_16x16x32_bf16 v[76:79], v[176:179], v[234:237], 0
	v_mfma_f32_16x16x32_bf16 v[72:75], v[184:187], v[234:237], 0
	v_mfma_f32_16x16x32_bf16 v[124:127], v[180:183], v[212:215], v[124:127]
	v_mfma_f32_16x16x32_bf16 v[120:123], v[188:191], v[212:215], v[120:123]
	v_mfma_f32_16x16x32_bf16 v[108:111], v[180:183], v[220:223], v[108:111]
	v_mfma_f32_16x16x32_bf16 v[104:107], v[188:191], v[220:223], v[104:107]
	v_mfma_f32_16x16x32_bf16 v[92:95], v[180:183], v[230:233], v[92:95]
	v_mfma_f32_16x16x32_bf16 v[88:91], v[188:191], v[230:233], v[88:91]
	v_mfma_f32_16x16x32_bf16 v[76:79], v[180:183], v[238:241], v[76:79]
	v_mfma_f32_16x16x32_bf16 v[72:75], v[188:191], v[238:241], v[72:75]


	v_mfma_f32_16x16x32_bf16 v[116:119], v[192:195], v[208:211], 0
	v_mfma_f32_16x16x32_bf16 v[112:115], v[200:203], v[208:211], 0
	v_mfma_f32_16x16x32_bf16 v[100:103], v[192:195], v[216:219], 0
	v_mfma_f32_16x16x32_bf16 v[96:99], v[200:203], v[216:219], 0
	v_mfma_f32_16x16x32_bf16 v[84:87], v[192:195], v[224:227], 0
	v_mfma_f32_16x16x32_bf16 v[80:83], v[200:203], v[224:227], 0
	v_mfma_f32_16x16x32_bf16 v[68:71], v[192:195], v[234:237], 0
	v_mfma_f32_16x16x32_bf16 v[64:67], v[200:203], v[234:237], 0
	v_mfma_f32_16x16x32_bf16 v[116:119], v[196:199], v[212:215], v[116:119]
	v_mfma_f32_16x16x32_bf16 v[112:115], v[204:207], v[212:215], v[112:115]
	v_mfma_f32_16x16x32_bf16 v[100:103], v[196:199], v[220:223], v[100:103]
	v_mfma_f32_16x16x32_bf16 v[96:99], v[204:207], v[220:223], v[96:99]
	v_mfma_f32_16x16x32_bf16 v[84:87], v[196:199], v[230:233], v[84:87]
	v_mfma_f32_16x16x32_bf16 v[80:83], v[204:207], v[230:233], v[80:83]
	v_mfma_f32_16x16x32_bf16 v[68:71], v[196:199], v[238:241], v[68:71]
	v_mfma_f32_16x16x32_bf16 v[64:67], v[204:207], v[238:241], v[64:67]
	s_setprio 0
	s_barrier
	s_add_i32 s54, s46, s35
	s_mov_b32 m0, s54
	ds_read_b128 v[208:211], v167 offset:16384
	ds_read_b128 v[212:215], v167 offset:17408
	ds_read_b128 v[216:219], v167 offset:18432
	ds_read_b128 v[220:223], v167 offset:19456
	ds_read_b128 v[224:227], v167 offset:20480
	ds_read_b128 v[230:233], v167 offset:21504
	ds_read_b128 v[234:237], v167 offset:22528
	ds_read_b128 v[238:241], v167 offset:23552
	global_load_lds_dwordx4 v130, s[28:29]
	s_add_i32 m0, s54, 0x2000
	s_add_u32 s54, s28, 0x40000
	s_addc_u32 s55, s29, 0
	s_add_i32 s56, s47, s35
	global_load_lds_dwordx4 v134, s[28:29]
	s_mov_b32 m0, s56
	s_nop 0
	global_load_lds_dwordx4 v130, s[54:55]
	s_add_i32 m0, s56, 0x2000
	s_nop 0
	global_load_lds_dwordx4 v134, s[54:55]
	s_mov_b32 m0, s36
	s_nop 0
	global_load_lds_dwordx4 v128, s[30:31]
	s_mov_b32 m0, s37
	s_nop 0
	global_load_lds_dwordx4 v132, s[30:31]
	s_add_u32 s86, s30, s4
	s_addc_u32 s87, s31, s5
	s_add_u32 s84, s28, s4
	s_addc_u32 s85, s29, s5
	s_waitcnt vmcnt(8)
	s_waitcnt lgkmcnt(0)
	s_barrier
	s_setprio 1
	s_waitcnt lgkmcnt(0)
	v_mfma_f32_16x16x32_bf16 v[60:63], v[176:179], v[208:211], 0
	v_mfma_f32_16x16x32_bf16 v[56:59], v[184:187], v[208:211], 0
	v_mfma_f32_16x16x32_bf16 v[44:47], v[176:179], v[216:219], 0
	v_mfma_f32_16x16x32_bf16 v[40:43], v[184:187], v[216:219], 0
	v_mfma_f32_16x16x32_bf16 v[28:31], v[176:179], v[224:227], 0
	v_mfma_f32_16x16x32_bf16 v[24:27], v[184:187], v[224:227], 0
	v_mfma_f32_16x16x32_bf16 v[12:15], v[176:179], v[234:237], 0
	v_mfma_f32_16x16x32_bf16 v[8:11], v[184:187], v[234:237], 0
	v_mfma_f32_16x16x32_bf16 v[60:63], v[180:183], v[212:215], v[60:63]
	v_mfma_f32_16x16x32_bf16 v[56:59], v[188:191], v[212:215], v[56:59]
	v_mfma_f32_16x16x32_bf16 v[44:47], v[180:183], v[220:223], v[44:47]
	v_mfma_f32_16x16x32_bf16 v[40:43], v[188:191], v[220:223], v[40:43]
	v_mfma_f32_16x16x32_bf16 v[28:31], v[180:183], v[230:233], v[28:31]
	v_mfma_f32_16x16x32_bf16 v[24:27], v[188:191], v[230:233], v[24:27]
	v_mfma_f32_16x16x32_bf16 v[12:15], v[180:183], v[238:241], v[12:15]
	v_mfma_f32_16x16x32_bf16 v[8:11], v[188:191], v[238:241], v[8:11]


	v_mfma_f32_16x16x32_bf16 v[52:55], v[192:195], v[208:211], 0
	v_mfma_f32_16x16x32_bf16 v[48:51], v[200:203], v[208:211], 0
	v_mfma_f32_16x16x32_bf16 v[36:39], v[192:195], v[216:219], 0
	v_mfma_f32_16x16x32_bf16 v[32:35], v[200:203], v[216:219], 0
	v_mfma_f32_16x16x32_bf16 v[20:23], v[192:195], v[224:227], 0
	v_mfma_f32_16x16x32_bf16 v[16:19], v[200:203], v[224:227], 0
	v_mfma_f32_16x16x32_bf16 v[4:7], v[192:195], v[234:237], 0
	v_mfma_f32_16x16x32_bf16 v[0:3], v[200:203], v[234:237], 0
	v_mfma_f32_16x16x32_bf16 v[52:55], v[196:199], v[212:215], v[52:55]
	v_mfma_f32_16x16x32_bf16 v[48:51], v[204:207], v[212:215], v[48:51]
	v_mfma_f32_16x16x32_bf16 v[36:39], v[196:199], v[220:223], v[36:39]
	v_mfma_f32_16x16x32_bf16 v[32:35], v[204:207], v[220:223], v[32:35]
	v_mfma_f32_16x16x32_bf16 v[20:23], v[196:199], v[230:233], v[20:23]
	v_mfma_f32_16x16x32_bf16 v[16:19], v[204:207], v[230:233], v[16:19]
	v_mfma_f32_16x16x32_bf16 v[4:7], v[196:199], v[238:241], v[4:7]
	v_mfma_f32_16x16x32_bf16 v[0:3], v[204:207], v[238:241], v[0:3]
	s_setprio 0
	s_barrier
	s_add_i32 s54, 0, 0x18000
	s_add_i32 s55, 0, 0x1c000
	v_add_u32_e32 v188, s54, v165
	v_add_u32_e32 v204, s55, v165
	ds_read_b128 v[176:179], v188
	ds_read_b128 v[180:183], v188 offset:1024
	ds_read_b128 v[184:187], v188 offset:2048
	ds_read_b128 v[188:191], v188 offset:3072
	ds_read_b128 v[192:195], v204
	ds_read_b128 v[196:199], v204 offset:1024
	ds_read_b128 v[200:203], v204 offset:2048
	ds_read_b128 v[204:207], v204 offset:3072
	s_add_u32 s30, s30, 0x40000
	s_addc_u32 s31, s31, 0
	s_mov_b32 m0, s41
	ds_read_b128 v[208:211], v167 offset:32768
	ds_read_b128 v[212:215], v167 offset:33792
	ds_read_b128 v[216:219], v167 offset:34816
	ds_read_b128 v[220:223], v167 offset:35840
	ds_read_b128 v[224:227], v167 offset:36864
	ds_read_b128 v[230:233], v167 offset:37888
	ds_read_b128 v[234:237], v167 offset:38912
	ds_read_b128 v[238:241], v167 offset:39936
	global_load_lds_dwordx4 v128, s[30:31]
	s_mov_b32 m0, s42
	s_nop 0
	global_load_lds_dwordx4 v132, s[30:31]
	s_waitcnt vmcnt(8)
	s_waitcnt lgkmcnt(0)
	s_barrier
	s_setprio 1
	s_waitcnt lgkmcnt(0)
	v_mfma_f32_16x16x32_bf16 v[124:127], v[176:179], v[208:211], v[124:127]
	v_mfma_f32_16x16x32_bf16 v[120:123], v[184:187], v[208:211], v[120:123]
	v_mfma_f32_16x16x32_bf16 v[108:111], v[176:179], v[216:219], v[108:111]
	v_mfma_f32_16x16x32_bf16 v[104:107], v[184:187], v[216:219], v[104:107]
	v_mfma_f32_16x16x32_bf16 v[92:95], v[176:179], v[224:227], v[92:95]
	v_mfma_f32_16x16x32_bf16 v[88:91], v[184:187], v[224:227], v[88:91]
	v_mfma_f32_16x16x32_bf16 v[76:79], v[176:179], v[234:237], v[76:79]
	v_mfma_f32_16x16x32_bf16 v[72:75], v[184:187], v[234:237], v[72:75]
	v_mfma_f32_16x16x32_bf16 v[124:127], v[180:183], v[212:215], v[124:127]
	v_mfma_f32_16x16x32_bf16 v[120:123], v[188:191], v[212:215], v[120:123]
	v_mfma_f32_16x16x32_bf16 v[108:111], v[180:183], v[220:223], v[108:111]
	v_mfma_f32_16x16x32_bf16 v[104:107], v[188:191], v[220:223], v[104:107]
	v_mfma_f32_16x16x32_bf16 v[92:95], v[180:183], v[230:233], v[92:95]
	v_mfma_f32_16x16x32_bf16 v[88:91], v[188:191], v[230:233], v[88:91]
	v_mfma_f32_16x16x32_bf16 v[76:79], v[180:183], v[238:241], v[76:79]
	v_mfma_f32_16x16x32_bf16 v[72:75], v[188:191], v[238:241], v[72:75]


	v_mfma_f32_16x16x32_bf16 v[116:119], v[192:195], v[208:211], v[116:119]
	v_mfma_f32_16x16x32_bf16 v[112:115], v[200:203], v[208:211], v[112:115]
	v_mfma_f32_16x16x32_bf16 v[100:103], v[192:195], v[216:219], v[100:103]
	v_mfma_f32_16x16x32_bf16 v[96:99], v[200:203], v[216:219], v[96:99]
	v_mfma_f32_16x16x32_bf16 v[84:87], v[192:195], v[224:227], v[84:87]
	v_mfma_f32_16x16x32_bf16 v[80:83], v[200:203], v[224:227], v[80:83]
	v_mfma_f32_16x16x32_bf16 v[68:71], v[192:195], v[234:237], v[68:71]
	v_mfma_f32_16x16x32_bf16 v[64:67], v[200:203], v[234:237], v[64:67]
	v_mfma_f32_16x16x32_bf16 v[116:119], v[196:199], v[212:215], v[116:119]
	v_mfma_f32_16x16x32_bf16 v[112:115], v[204:207], v[212:215], v[112:115]
	v_mfma_f32_16x16x32_bf16 v[100:103], v[196:199], v[220:223], v[100:103]
	v_mfma_f32_16x16x32_bf16 v[96:99], v[204:207], v[220:223], v[96:99]
	v_mfma_f32_16x16x32_bf16 v[84:87], v[196:199], v[230:233], v[84:87]
	v_mfma_f32_16x16x32_bf16 v[80:83], v[204:207], v[230:233], v[80:83]
	v_mfma_f32_16x16x32_bf16 v[68:71], v[196:199], v[238:241], v[68:71]
	v_mfma_f32_16x16x32_bf16 v[64:67], v[204:207], v[238:241], v[64:67]
	s_setprio 0
	s_barrier
	s_add_i32 s30, s54, s35
	s_mov_b32 m0, s30
	ds_read_b128 v[208:211], v167 offset:49152
	ds_read_b128 v[212:215], v167 offset:50176
	ds_read_b128 v[216:219], v167 offset:51200
	ds_read_b128 v[220:223], v167 offset:52224
	ds_read_b128 v[224:227], v167 offset:53248
	ds_read_b128 v[230:233], v167 offset:54272
	ds_read_b128 v[234:237], v167 offset:55296
	ds_read_b128 v[238:241], v167 offset:56320
	global_load_lds_dwordx4 v130, s[84:85]
	s_add_i32 m0, s30, 0x2000
	s_add_u32 s28, s28, 0x40080
	s_addc_u32 s29, s29, 0
	s_add_i32 s30, s55, s35
	global_load_lds_dwordx4 v134, s[84:85]
	s_mov_b32 m0, s30
	s_nop 0
	global_load_lds_dwordx4 v130, s[28:29]
	s_add_i32 m0, s30, 0x2000
	s_nop 0
	global_load_lds_dwordx4 v134, s[28:29]
	s_mov_b32 m0, s44
	s_nop 0
	global_load_lds_dwordx4 v128, s[86:87]
	s_mov_b32 m0, s45
	s_nop 0
	global_load_lds_dwordx4 v132, s[86:87]
	s_waitcnt vmcnt(8)
	s_waitcnt lgkmcnt(0)
	s_barrier
	s_setprio 1
	s_waitcnt lgkmcnt(0)
	v_mfma_f32_16x16x32_bf16 v[60:63], v[176:179], v[208:211], v[60:63]
	v_mfma_f32_16x16x32_bf16 v[56:59], v[184:187], v[208:211], v[56:59]
	v_mfma_f32_16x16x32_bf16 v[44:47], v[176:179], v[216:219], v[44:47]
	v_mfma_f32_16x16x32_bf16 v[40:43], v[184:187], v[216:219], v[40:43]
	v_mfma_f32_16x16x32_bf16 v[28:31], v[176:179], v[224:227], v[28:31]
	v_mfma_f32_16x16x32_bf16 v[24:27], v[184:187], v[224:227], v[24:27]
	v_mfma_f32_16x16x32_bf16 v[12:15], v[176:179], v[234:237], v[12:15]
	v_mfma_f32_16x16x32_bf16 v[8:11], v[184:187], v[234:237], v[8:11]
	v_mfma_f32_16x16x32_bf16 v[60:63], v[180:183], v[212:215], v[60:63]
	v_mfma_f32_16x16x32_bf16 v[56:59], v[188:191], v[212:215], v[56:59]
	v_mfma_f32_16x16x32_bf16 v[44:47], v[180:183], v[220:223], v[44:47]
	v_mfma_f32_16x16x32_bf16 v[40:43], v[188:191], v[220:223], v[40:43]
	v_mfma_f32_16x16x32_bf16 v[28:31], v[180:183], v[230:233], v[28:31]
	v_mfma_f32_16x16x32_bf16 v[24:27], v[188:191], v[230:233], v[24:27]
	v_mfma_f32_16x16x32_bf16 v[12:15], v[180:183], v[238:241], v[12:15]
	v_mfma_f32_16x16x32_bf16 v[8:11], v[188:191], v[238:241], v[8:11]


	v_mfma_f32_16x16x32_bf16 v[52:55], v[192:195], v[208:211], v[52:55]
	v_mfma_f32_16x16x32_bf16 v[48:51], v[200:203], v[208:211], v[48:51]
	v_mfma_f32_16x16x32_bf16 v[36:39], v[192:195], v[216:219], v[36:39]
	v_mfma_f32_16x16x32_bf16 v[32:35], v[200:203], v[216:219], v[32:35]
	v_mfma_f32_16x16x32_bf16 v[20:23], v[192:195], v[224:227], v[20:23]
	v_mfma_f32_16x16x32_bf16 v[16:19], v[200:203], v[224:227], v[16:19]
	v_mfma_f32_16x16x32_bf16 v[4:7], v[192:195], v[234:237], v[4:7]
	v_mfma_f32_16x16x32_bf16 v[0:3], v[200:203], v[234:237], v[0:3]
	v_mfma_f32_16x16x32_bf16 v[52:55], v[196:199], v[212:215], v[52:55]
	v_mfma_f32_16x16x32_bf16 v[48:51], v[204:207], v[212:215], v[48:51]
	v_mfma_f32_16x16x32_bf16 v[36:39], v[196:199], v[220:223], v[36:39]
	v_mfma_f32_16x16x32_bf16 v[32:35], v[204:207], v[220:223], v[32:35]
	v_mfma_f32_16x16x32_bf16 v[20:23], v[196:199], v[230:233], v[20:23]
	v_mfma_f32_16x16x32_bf16 v[16:19], v[204:207], v[230:233], v[16:19]
	v_mfma_f32_16x16x32_bf16 v[4:7], v[196:199], v[238:241], v[4:7]
	v_mfma_f32_16x16x32_bf16 v[0:3], v[204:207], v[238:241], v[0:3]
	s_setprio 0
	s_barrier
	s_add_i32 s53, s53, 2
	s_add_u32 s26, s26, 0x100
	s_addc_u32 s27, s27, 0
	s_add_u32 s51, s51, 0x100
	s_addc_u32 s52, s52, 0
	s_branch .LBB0_499
.LBB0_498:
	v_add_u32_e32 v188, s46, v165
	v_add_u32_e32 v204, s47, v165
	ds_read_b128 v[176:179], v188
	ds_read_b128 v[180:183], v188 offset:1024
	ds_read_b128 v[184:187], v188 offset:2048
	ds_read_b128 v[188:191], v188 offset:3072
	ds_read_b128 v[192:195], v204
	ds_read_b128 v[196:199], v204 offset:1024
	ds_read_b128 v[200:203], v204 offset:2048
	ds_read_b128 v[204:207], v204 offset:3072
	s_add_u32 s30, s26, 0xfffc0080
	s_addc_u32 s31, s27, -1
	s_and_b64 s[28:29], s[28:29], exec
	s_cselect_b32 s31, s11, s31
	s_cselect_b32 s30, s49, s30
	s_cselect_b32 s29, s9, s52
	s_cselect_b32 s28, s50, s51
	s_add_i32 m0, s36, 0xc000
	ds_read_b128 v[208:211], v167
	ds_read_b128 v[212:215], v167 offset:1024
	ds_read_b128 v[216:219], v167 offset:2048
	ds_read_b128 v[220:223], v167 offset:3072
	ds_read_b128 v[224:227], v167 offset:4096
	ds_read_b128 v[230:233], v167 offset:5120
	ds_read_b128 v[234:237], v167 offset:6144
	ds_read_b128 v[238:241], v167 offset:7168
	global_load_lds_dwordx4 v136, s[26:27]
	s_add_i32 m0, s36, 0xe000
	s_nop 0
	global_load_lds_dwordx4 v138, s[26:27]
	s_waitcnt vmcnt(8)
	s_waitcnt lgkmcnt(0)
	s_barrier
	s_setprio 1
	s_waitcnt lgkmcnt(0)
	v_mfma_f32_16x16x32_bf16 v[124:127], v[176:179], v[208:211], v[124:127]
	v_mfma_f32_16x16x32_bf16 v[120:123], v[184:187], v[208:211], v[120:123]
	v_mfma_f32_16x16x32_bf16 v[108:111], v[176:179], v[216:219], v[108:111]
	v_mfma_f32_16x16x32_bf16 v[104:107], v[184:187], v[216:219], v[104:107]
	v_mfma_f32_16x16x32_bf16 v[92:95], v[176:179], v[224:227], v[92:95]
	v_mfma_f32_16x16x32_bf16 v[88:91], v[184:187], v[224:227], v[88:91]
	v_mfma_f32_16x16x32_bf16 v[76:79], v[176:179], v[234:237], v[76:79]
	v_mfma_f32_16x16x32_bf16 v[72:75], v[184:187], v[234:237], v[72:75]
	v_mfma_f32_16x16x32_bf16 v[124:127], v[180:183], v[212:215], v[124:127]
	v_mfma_f32_16x16x32_bf16 v[120:123], v[188:191], v[212:215], v[120:123]
	v_mfma_f32_16x16x32_bf16 v[108:111], v[180:183], v[220:223], v[108:111]
	v_mfma_f32_16x16x32_bf16 v[104:107], v[188:191], v[220:223], v[104:107]
	v_mfma_f32_16x16x32_bf16 v[92:95], v[180:183], v[230:233], v[92:95]
	v_mfma_f32_16x16x32_bf16 v[88:91], v[188:191], v[230:233], v[88:91]
	v_mfma_f32_16x16x32_bf16 v[76:79], v[180:183], v[238:241], v[76:79]
	v_mfma_f32_16x16x32_bf16 v[72:75], v[188:191], v[238:241], v[72:75]


	v_mfma_f32_16x16x32_bf16 v[116:119], v[192:195], v[208:211], v[116:119]
	v_mfma_f32_16x16x32_bf16 v[112:115], v[200:203], v[208:211], v[112:115]
	v_mfma_f32_16x16x32_bf16 v[100:103], v[192:195], v[216:219], v[100:103]
	v_mfma_f32_16x16x32_bf16 v[96:99], v[200:203], v[216:219], v[96:99]
	v_mfma_f32_16x16x32_bf16 v[84:87], v[192:195], v[224:227], v[84:87]
	v_mfma_f32_16x16x32_bf16 v[80:83], v[200:203], v[224:227], v[80:83]
	v_mfma_f32_16x16x32_bf16 v[68:71], v[192:195], v[234:237], v[68:71]
	v_mfma_f32_16x16x32_bf16 v[64:67], v[200:203], v[234:237], v[64:67]
	v_mfma_f32_16x16x32_bf16 v[116:119], v[196:199], v[212:215], v[116:119]
	v_mfma_f32_16x16x32_bf16 v[112:115], v[204:207], v[212:215], v[112:115]
	v_mfma_f32_16x16x32_bf16 v[100:103], v[196:199], v[220:223], v[100:103]
	v_mfma_f32_16x16x32_bf16 v[96:99], v[204:207], v[220:223], v[96:99]
	v_mfma_f32_16x16x32_bf16 v[84:87], v[196:199], v[230:233], v[84:87]
	v_mfma_f32_16x16x32_bf16 v[80:83], v[204:207], v[230:233], v[80:83]
	v_mfma_f32_16x16x32_bf16 v[68:71], v[196:199], v[238:241], v[68:71]
	v_mfma_f32_16x16x32_bf16 v[64:67], v[204:207], v[238:241], v[64:67]
	s_setprio 0
	s_barrier
	s_add_i32 s54, s46, s35
	s_mov_b32 m0, s54
	ds_read_b128 v[208:211], v167 offset:16384
	ds_read_b128 v[212:215], v167 offset:17408
	ds_read_b128 v[216:219], v167 offset:18432
	ds_read_b128 v[220:223], v167 offset:19456
	ds_read_b128 v[224:227], v167 offset:20480
	ds_read_b128 v[230:233], v167 offset:21504
	ds_read_b128 v[234:237], v167 offset:22528
	ds_read_b128 v[238:241], v167 offset:23552
	global_load_lds_dwordx4 v130, s[28:29]
	s_add_i32 m0, s54, 0x2000
	s_add_u32 s54, s28, 0x40000
	s_addc_u32 s55, s29, 0
	s_add_i32 s56, s47, s35
	global_load_lds_dwordx4 v134, s[28:29]
	s_mov_b32 m0, s56
	s_nop 0
	global_load_lds_dwordx4 v130, s[54:55]
	s_add_i32 m0, s56, 0x2000
	s_nop 0
	global_load_lds_dwordx4 v134, s[54:55]
	s_mov_b32 m0, s36
	s_nop 0
	global_load_lds_dwordx4 v128, s[30:31]
	s_mov_b32 m0, s37
	s_nop 0
	global_load_lds_dwordx4 v132, s[30:31]
	s_add_u32 s86, s30, s4
	s_addc_u32 s87, s31, s5
	s_add_u32 s84, s28, s4
	s_addc_u32 s85, s29, s5
	s_waitcnt vmcnt(8)
	s_waitcnt lgkmcnt(0)
	s_barrier
	s_setprio 1
	s_waitcnt lgkmcnt(0)
	v_mfma_f32_16x16x32_bf16 v[60:63], v[176:179], v[208:211], v[60:63]
	v_mfma_f32_16x16x32_bf16 v[56:59], v[184:187], v[208:211], v[56:59]
	v_mfma_f32_16x16x32_bf16 v[44:47], v[176:179], v[216:219], v[44:47]
	v_mfma_f32_16x16x32_bf16 v[40:43], v[184:187], v[216:219], v[40:43]
	v_mfma_f32_16x16x32_bf16 v[28:31], v[176:179], v[224:227], v[28:31]
	v_mfma_f32_16x16x32_bf16 v[24:27], v[184:187], v[224:227], v[24:27]
	v_mfma_f32_16x16x32_bf16 v[12:15], v[176:179], v[234:237], v[12:15]
	v_mfma_f32_16x16x32_bf16 v[8:11], v[184:187], v[234:237], v[8:11]
	v_mfma_f32_16x16x32_bf16 v[60:63], v[180:183], v[212:215], v[60:63]
	v_mfma_f32_16x16x32_bf16 v[56:59], v[188:191], v[212:215], v[56:59]
	v_mfma_f32_16x16x32_bf16 v[44:47], v[180:183], v[220:223], v[44:47]
	v_mfma_f32_16x16x32_bf16 v[40:43], v[188:191], v[220:223], v[40:43]
	v_mfma_f32_16x16x32_bf16 v[28:31], v[180:183], v[230:233], v[28:31]
	v_mfma_f32_16x16x32_bf16 v[24:27], v[188:191], v[230:233], v[24:27]
	v_mfma_f32_16x16x32_bf16 v[12:15], v[180:183], v[238:241], v[12:15]
	v_mfma_f32_16x16x32_bf16 v[8:11], v[188:191], v[238:241], v[8:11]


	v_mfma_f32_16x16x32_bf16 v[52:55], v[192:195], v[208:211], v[52:55]
	v_mfma_f32_16x16x32_bf16 v[48:51], v[200:203], v[208:211], v[48:51]
	v_mfma_f32_16x16x32_bf16 v[36:39], v[192:195], v[216:219], v[36:39]
	v_mfma_f32_16x16x32_bf16 v[32:35], v[200:203], v[216:219], v[32:35]
	v_mfma_f32_16x16x32_bf16 v[20:23], v[192:195], v[224:227], v[20:23]
	v_mfma_f32_16x16x32_bf16 v[16:19], v[200:203], v[224:227], v[16:19]
	v_mfma_f32_16x16x32_bf16 v[4:7], v[192:195], v[234:237], v[4:7]
	v_mfma_f32_16x16x32_bf16 v[0:3], v[200:203], v[234:237], v[0:3]
	v_mfma_f32_16x16x32_bf16 v[52:55], v[196:199], v[212:215], v[52:55]
	v_mfma_f32_16x16x32_bf16 v[48:51], v[204:207], v[212:215], v[48:51]
	v_mfma_f32_16x16x32_bf16 v[36:39], v[196:199], v[220:223], v[36:39]
	v_mfma_f32_16x16x32_bf16 v[32:35], v[204:207], v[220:223], v[32:35]
	v_mfma_f32_16x16x32_bf16 v[20:23], v[196:199], v[230:233], v[20:23]
	v_mfma_f32_16x16x32_bf16 v[16:19], v[204:207], v[230:233], v[16:19]
	v_mfma_f32_16x16x32_bf16 v[4:7], v[196:199], v[238:241], v[4:7]
	v_mfma_f32_16x16x32_bf16 v[0:3], v[204:207], v[238:241], v[0:3]
	s_setprio 0
	s_barrier
	s_add_i32 s54, 0, 0x18000
	s_add_i32 s55, 0, 0x1c000
	v_add_u32_e32 v188, s54, v165
	v_add_u32_e32 v204, s55, v165
	ds_read_b128 v[176:179], v188
	ds_read_b128 v[180:183], v188 offset:1024
	ds_read_b128 v[184:187], v188 offset:2048
	ds_read_b128 v[188:191], v188 offset:3072
	ds_read_b128 v[192:195], v204
	ds_read_b128 v[196:199], v204 offset:1024
	ds_read_b128 v[200:203], v204 offset:2048
	ds_read_b128 v[204:207], v204 offset:3072
	s_add_u32 s30, s30, 0x40000
	s_addc_u32 s31, s31, 0
	s_mov_b32 m0, s41
	ds_read_b128 v[208:211], v167 offset:32768
	ds_read_b128 v[212:215], v167 offset:33792
	ds_read_b128 v[216:219], v167 offset:34816
	ds_read_b128 v[220:223], v167 offset:35840
	ds_read_b128 v[224:227], v167 offset:36864
	ds_read_b128 v[230:233], v167 offset:37888
	ds_read_b128 v[234:237], v167 offset:38912
	ds_read_b128 v[238:241], v167 offset:39936
	global_load_lds_dwordx4 v128, s[30:31]
	s_mov_b32 m0, s42
	s_nop 0
	global_load_lds_dwordx4 v132, s[30:31]
	s_waitcnt vmcnt(8)
	s_waitcnt lgkmcnt(0)
	s_barrier
	s_setprio 1
	s_waitcnt lgkmcnt(0)
	v_mfma_f32_16x16x32_bf16 v[124:127], v[176:179], v[208:211], v[124:127]
	v_mfma_f32_16x16x32_bf16 v[120:123], v[184:187], v[208:211], v[120:123]
	v_mfma_f32_16x16x32_bf16 v[108:111], v[176:179], v[216:219], v[108:111]
	v_mfma_f32_16x16x32_bf16 v[104:107], v[184:187], v[216:219], v[104:107]
	v_mfma_f32_16x16x32_bf16 v[92:95], v[176:179], v[224:227], v[92:95]
	v_mfma_f32_16x16x32_bf16 v[88:91], v[184:187], v[224:227], v[88:91]
	v_mfma_f32_16x16x32_bf16 v[76:79], v[176:179], v[234:237], v[76:79]
	v_mfma_f32_16x16x32_bf16 v[72:75], v[184:187], v[234:237], v[72:75]
	v_mfma_f32_16x16x32_bf16 v[124:127], v[180:183], v[212:215], v[124:127]
	v_mfma_f32_16x16x32_bf16 v[120:123], v[188:191], v[212:215], v[120:123]
	v_mfma_f32_16x16x32_bf16 v[108:111], v[180:183], v[220:223], v[108:111]
	v_mfma_f32_16x16x32_bf16 v[104:107], v[188:191], v[220:223], v[104:107]
	v_mfma_f32_16x16x32_bf16 v[92:95], v[180:183], v[230:233], v[92:95]
	v_mfma_f32_16x16x32_bf16 v[88:91], v[188:191], v[230:233], v[88:91]
	v_mfma_f32_16x16x32_bf16 v[76:79], v[180:183], v[238:241], v[76:79]
	v_mfma_f32_16x16x32_bf16 v[72:75], v[188:191], v[238:241], v[72:75]


	v_mfma_f32_16x16x32_bf16 v[116:119], v[192:195], v[208:211], v[116:119]
	v_mfma_f32_16x16x32_bf16 v[112:115], v[200:203], v[208:211], v[112:115]
	v_mfma_f32_16x16x32_bf16 v[100:103], v[192:195], v[216:219], v[100:103]
	v_mfma_f32_16x16x32_bf16 v[96:99], v[200:203], v[216:219], v[96:99]
	v_mfma_f32_16x16x32_bf16 v[84:87], v[192:195], v[224:227], v[84:87]
	v_mfma_f32_16x16x32_bf16 v[80:83], v[200:203], v[224:227], v[80:83]
	v_mfma_f32_16x16x32_bf16 v[68:71], v[192:195], v[234:237], v[68:71]
	v_mfma_f32_16x16x32_bf16 v[64:67], v[200:203], v[234:237], v[64:67]
	v_mfma_f32_16x16x32_bf16 v[116:119], v[196:199], v[212:215], v[116:119]
	v_mfma_f32_16x16x32_bf16 v[112:115], v[204:207], v[212:215], v[112:115]
	v_mfma_f32_16x16x32_bf16 v[100:103], v[196:199], v[220:223], v[100:103]
	v_mfma_f32_16x16x32_bf16 v[96:99], v[204:207], v[220:223], v[96:99]
	v_mfma_f32_16x16x32_bf16 v[84:87], v[196:199], v[230:233], v[84:87]
	v_mfma_f32_16x16x32_bf16 v[80:83], v[204:207], v[230:233], v[80:83]
	v_mfma_f32_16x16x32_bf16 v[68:71], v[196:199], v[238:241], v[68:71]
	v_mfma_f32_16x16x32_bf16 v[64:67], v[204:207], v[238:241], v[64:67]
	s_setprio 0
	s_barrier
	s_add_i32 s30, s54, s35
	s_mov_b32 m0, s30
	ds_read_b128 v[208:211], v167 offset:49152
	ds_read_b128 v[212:215], v167 offset:50176
	ds_read_b128 v[216:219], v167 offset:51200
	ds_read_b128 v[220:223], v167 offset:52224
	ds_read_b128 v[224:227], v167 offset:53248
	ds_read_b128 v[230:233], v167 offset:54272
	ds_read_b128 v[234:237], v167 offset:55296
	ds_read_b128 v[238:241], v167 offset:56320
	global_load_lds_dwordx4 v130, s[84:85]
	s_add_i32 m0, s30, 0x2000
	s_add_u32 s28, s28, 0x40080
	s_addc_u32 s29, s29, 0
	s_add_i32 s30, s55, s35
	global_load_lds_dwordx4 v134, s[84:85]
	s_mov_b32 m0, s30
	s_nop 0
	global_load_lds_dwordx4 v130, s[28:29]
	s_add_i32 m0, s30, 0x2000
	s_nop 0
	global_load_lds_dwordx4 v134, s[28:29]
	s_mov_b32 m0, s44
	s_nop 0
	global_load_lds_dwordx4 v128, s[86:87]
	s_mov_b32 m0, s45
	s_nop 0
	global_load_lds_dwordx4 v132, s[86:87]
	s_waitcnt vmcnt(8)
	s_waitcnt lgkmcnt(0)
	s_barrier
	s_setprio 1
	s_waitcnt lgkmcnt(0)
	v_mfma_f32_16x16x32_bf16 v[60:63], v[176:179], v[208:211], v[60:63]
	v_mfma_f32_16x16x32_bf16 v[56:59], v[184:187], v[208:211], v[56:59]
	v_mfma_f32_16x16x32_bf16 v[44:47], v[176:179], v[216:219], v[44:47]
	v_mfma_f32_16x16x32_bf16 v[40:43], v[184:187], v[216:219], v[40:43]
	v_mfma_f32_16x16x32_bf16 v[28:31], v[176:179], v[224:227], v[28:31]
	v_mfma_f32_16x16x32_bf16 v[24:27], v[184:187], v[224:227], v[24:27]
	v_mfma_f32_16x16x32_bf16 v[12:15], v[176:179], v[234:237], v[12:15]
	v_mfma_f32_16x16x32_bf16 v[8:11], v[184:187], v[234:237], v[8:11]
	v_mfma_f32_16x16x32_bf16 v[60:63], v[180:183], v[212:215], v[60:63]
	v_mfma_f32_16x16x32_bf16 v[56:59], v[188:191], v[212:215], v[56:59]
	v_mfma_f32_16x16x32_bf16 v[44:47], v[180:183], v[220:223], v[44:47]
	v_mfma_f32_16x16x32_bf16 v[40:43], v[188:191], v[220:223], v[40:43]
	v_mfma_f32_16x16x32_bf16 v[28:31], v[180:183], v[230:233], v[28:31]
	v_mfma_f32_16x16x32_bf16 v[24:27], v[188:191], v[230:233], v[24:27]
	v_mfma_f32_16x16x32_bf16 v[12:15], v[180:183], v[238:241], v[12:15]
	v_mfma_f32_16x16x32_bf16 v[8:11], v[188:191], v[238:241], v[8:11]


	v_mfma_f32_16x16x32_bf16 v[52:55], v[192:195], v[208:211], v[52:55]
	v_mfma_f32_16x16x32_bf16 v[48:51], v[200:203], v[208:211], v[48:51]
	v_mfma_f32_16x16x32_bf16 v[36:39], v[192:195], v[216:219], v[36:39]
	v_mfma_f32_16x16x32_bf16 v[32:35], v[200:203], v[216:219], v[32:35]
	v_mfma_f32_16x16x32_bf16 v[20:23], v[192:195], v[224:227], v[20:23]
	v_mfma_f32_16x16x32_bf16 v[16:19], v[200:203], v[224:227], v[16:19]
	v_mfma_f32_16x16x32_bf16 v[4:7], v[192:195], v[234:237], v[4:7]
	v_mfma_f32_16x16x32_bf16 v[0:3], v[200:203], v[234:237], v[0:3]
	v_mfma_f32_16x16x32_bf16 v[52:55], v[196:199], v[212:215], v[52:55]
	v_mfma_f32_16x16x32_bf16 v[48:51], v[204:207], v[212:215], v[48:51]
	v_mfma_f32_16x16x32_bf16 v[36:39], v[196:199], v[220:223], v[36:39]
	v_mfma_f32_16x16x32_bf16 v[32:35], v[204:207], v[220:223], v[32:35]
	v_mfma_f32_16x16x32_bf16 v[20:23], v[196:199], v[230:233], v[20:23]
	v_mfma_f32_16x16x32_bf16 v[16:19], v[204:207], v[230:233], v[16:19]
	v_mfma_f32_16x16x32_bf16 v[4:7], v[196:199], v[238:241], v[4:7]
	v_mfma_f32_16x16x32_bf16 v[0:3], v[204:207], v[238:241], v[0:3]
	s_setprio 0
	s_barrier
	s_add_i32 s53, s53, 2
	s_add_u32 s26, s26, 0x100
	s_addc_u32 s27, s27, 0
	s_add_u32 s51, s51, 0x100
	s_addc_u32 s52, s52, 0
	s_cmp_gt_u32 s53, 13
	s_cbranch_scc1 .LBB0_501

.LBB0_599:
	s_add_u32 s20, s50, s18
	s_addc_u32 s21, s51, s19
	s_add_u32 s20, s20, 0x1d80100
	s_addc_u32 s21, s21, 0
	s_add_u32 s55, s52, s18
	s_addc_u32 s56, s53, s19
	s_add_i32 s57, 0, 0x10000
	s_cmpk_eq_i32 s18, 0x1f00
	s_cselect_b32 s23, s11, s21
	s_cselect_b32 s22, s10, s20
	s_cselect_b32 s21, s1, s56
	s_cselect_b32 s20, s0, s55
	s_add_i32 s55, 0, 0x14000
	v_add_u32_e32 v152, s57, v138
	v_add_u32_e32 v168, s55, v138
	ds_read_b128 v[140:143], v152
	ds_read_b128 v[144:147], v152 offset:1024
	ds_read_b128 v[148:151], v152 offset:2048
	ds_read_b128 v[152:155], v152 offset:3072
	ds_read_b128 v[156:159], v168
	ds_read_b128 v[160:163], v168 offset:1024
	ds_read_b128 v[164:167], v168 offset:2048
	ds_read_b128 v[168:171], v168 offset:3072
	v_lshl_add_u64 v[180:181], v[134:135], 0, s[18:19]
	s_add_i32 m0, s43, 0xc000
	ds_read_b128 v[172:175], v139
	ds_read_b128 v[176:179], v139 offset:1024
	ds_read_b128 v[184:187], v139 offset:2048
	ds_read_b128 v[188:191], v139 offset:3072
	ds_read_b128 v[192:195], v139 offset:4096
	ds_read_b128 v[196:199], v139 offset:5120
	ds_read_b128 v[200:203], v139 offset:6144
	ds_read_b128 v[204:207], v139 offset:7168
	global_load_lds_dwordx4 v[180:181], off
	v_lshl_add_u64 v[180:181], v[136:137], 0, s[18:19]
	s_add_i32 m0, s43, 0xe000
	s_nop 0
	global_load_lds_dwordx4 v[180:181], off
	s_waitcnt vmcnt(8)
	s_waitcnt lgkmcnt(0)
	s_barrier
	s_setprio 1
	s_waitcnt lgkmcnt(0)
	v_mfma_f32_16x16x32_bf16 v[124:127], v[140:143], v[172:175], v[124:127]
	v_mfma_f32_16x16x32_bf16 v[120:123], v[148:151], v[172:175], v[120:123]
	v_mfma_f32_16x16x32_bf16 v[116:119], v[140:143], v[184:187], v[116:119]
	v_mfma_f32_16x16x32_bf16 v[112:115], v[148:151], v[184:187], v[112:115]
	v_mfma_f32_16x16x32_bf16 v[92:95], v[140:143], v[192:195], v[92:95]
	v_mfma_f32_16x16x32_bf16 v[88:91], v[148:151], v[192:195], v[88:91]
	v_mfma_f32_16x16x32_bf16 v[80:83], v[140:143], v[200:203], v[80:83]
	v_mfma_f32_16x16x32_bf16 v[72:75], v[148:151], v[200:203], v[72:75]
	v_mfma_f32_16x16x32_bf16 v[124:127], v[144:147], v[176:179], v[124:127]
	v_mfma_f32_16x16x32_bf16 v[120:123], v[152:155], v[176:179], v[120:123]
	v_mfma_f32_16x16x32_bf16 v[116:119], v[144:147], v[188:191], v[116:119]
	v_mfma_f32_16x16x32_bf16 v[112:115], v[152:155], v[188:191], v[112:115]
	v_mfma_f32_16x16x32_bf16 v[92:95], v[144:147], v[196:199], v[92:95]
	v_mfma_f32_16x16x32_bf16 v[88:91], v[152:155], v[196:199], v[88:91]
	v_mfma_f32_16x16x32_bf16 v[80:83], v[144:147], v[204:207], v[80:83]
	v_mfma_f32_16x16x32_bf16 v[72:75], v[152:155], v[204:207], v[72:75]


	v_mfma_f32_16x16x32_bf16 v[108:111], v[156:159], v[172:175], v[108:111]
	v_mfma_f32_16x16x32_bf16 v[104:107], v[164:167], v[172:175], v[104:107]
	v_mfma_f32_16x16x32_bf16 v[100:103], v[156:159], v[184:187], v[100:103]
	v_mfma_f32_16x16x32_bf16 v[96:99], v[164:167], v[184:187], v[96:99]
	v_mfma_f32_16x16x32_bf16 v[84:87], v[156:159], v[192:195], v[84:87]
	v_mfma_f32_16x16x32_bf16 v[76:79], v[164:167], v[192:195], v[76:79]
	v_mfma_f32_16x16x32_bf16 v[68:71], v[156:159], v[200:203], v[68:71]
	v_mfma_f32_16x16x32_bf16 v[64:67], v[164:167], v[200:203], v[64:67]
	v_mfma_f32_16x16x32_bf16 v[108:111], v[160:163], v[176:179], v[108:111]
	v_mfma_f32_16x16x32_bf16 v[104:107], v[168:171], v[176:179], v[104:107]
	v_mfma_f32_16x16x32_bf16 v[100:103], v[160:163], v[188:191], v[100:103]
	v_mfma_f32_16x16x32_bf16 v[96:99], v[168:171], v[188:191], v[96:99]
	v_mfma_f32_16x16x32_bf16 v[84:87], v[160:163], v[196:199], v[84:87]
	v_mfma_f32_16x16x32_bf16 v[76:79], v[168:171], v[196:199], v[76:79]
	v_mfma_f32_16x16x32_bf16 v[68:71], v[160:163], v[204:207], v[68:71]
	v_mfma_f32_16x16x32_bf16 v[64:67], v[168:171], v[204:207], v[64:67]
	s_setprio 0
	s_barrier
	s_add_i32 s56, s57, s42
	s_mov_b32 m0, s56
	ds_read_b128 v[172:175], v139 offset:16384
	ds_read_b128 v[176:179], v139 offset:17408
	ds_read_b128 v[184:187], v139 offset:18432
	ds_read_b128 v[188:191], v139 offset:19456
	ds_read_b128 v[192:195], v139 offset:20480
	ds_read_b128 v[196:199], v139 offset:21504
	ds_read_b128 v[200:203], v139 offset:22528
	ds_read_b128 v[204:207], v139 offset:23552
	global_load_lds_dwordx4 v212, s[20:21]
	s_add_i32 m0, s56, 0x2000
	s_add_u32 s56, s20, 0x100000
	s_addc_u32 s57, s21, 0
	s_add_i32 s55, s55, s42
	global_load_lds_dwordx4 v128, s[20:21]
	s_mov_b32 m0, s55
	s_nop 0
	global_load_lds_dwordx4 v212, s[56:57]
	s_add_i32 m0, s55, 0x2000
	s_nop 0
	global_load_lds_dwordx4 v128, s[56:57]
	s_mov_b32 m0, s43
	s_nop 0
	global_load_lds_dwordx4 v132, s[22:23]
	s_mov_b32 m0, s44
	s_nop 0
	global_load_lds_dwordx4 v130, s[22:23]
	s_add_u32 s86, s22, s4
	s_addc_u32 s87, s23, s5
	s_add_u32 s84, s20, s4
	s_addc_u32 s85, s21, s5
	s_waitcnt vmcnt(8)
	s_waitcnt lgkmcnt(0)
	s_barrier
	s_setprio 1
	s_waitcnt lgkmcnt(0)
	v_mfma_f32_16x16x32_bf16 v[60:63], v[140:143], v[172:175], v[60:63]
	v_mfma_f32_16x16x32_bf16 v[56:59], v[148:151], v[172:175], v[56:59]
	v_mfma_f32_16x16x32_bf16 v[48:51], v[140:143], v[184:187], v[48:51]
	v_mfma_f32_16x16x32_bf16 v[40:43], v[148:151], v[184:187], v[40:43]
	v_mfma_f32_16x16x32_bf16 v[28:31], v[140:143], v[192:195], v[28:31]
	v_mfma_f32_16x16x32_bf16 v[24:27], v[148:151], v[192:195], v[24:27]
	v_mfma_f32_16x16x32_bf16 v[16:19], v[140:143], v[200:203], v[16:19]
	v_mfma_f32_16x16x32_bf16 v[8:11], v[148:151], v[200:203], v[8:11]
	v_mfma_f32_16x16x32_bf16 v[60:63], v[144:147], v[176:179], v[60:63]
	v_mfma_f32_16x16x32_bf16 v[56:59], v[152:155], v[176:179], v[56:59]
	v_mfma_f32_16x16x32_bf16 v[48:51], v[144:147], v[188:191], v[48:51]
	v_mfma_f32_16x16x32_bf16 v[40:43], v[152:155], v[188:191], v[40:43]
	v_mfma_f32_16x16x32_bf16 v[28:31], v[144:147], v[196:199], v[28:31]
	v_mfma_f32_16x16x32_bf16 v[24:27], v[152:155], v[196:199], v[24:27]
	v_mfma_f32_16x16x32_bf16 v[16:19], v[144:147], v[204:207], v[16:19]
	v_mfma_f32_16x16x32_bf16 v[8:11], v[152:155], v[204:207], v[8:11]


	v_mfma_f32_16x16x32_bf16 v[52:55], v[156:159], v[172:175], v[52:55]
	v_mfma_f32_16x16x32_bf16 v[44:47], v[164:167], v[172:175], v[44:47]
	v_mfma_f32_16x16x32_bf16 v[36:39], v[156:159], v[184:187], v[36:39]
	v_mfma_f32_16x16x32_bf16 v[32:35], v[164:167], v[184:187], v[32:35]
	v_mfma_f32_16x16x32_bf16 v[20:23], v[156:159], v[192:195], v[20:23]
	v_mfma_f32_16x16x32_bf16 v[12:15], v[164:167], v[192:195], v[12:15]
	v_mfma_f32_16x16x32_bf16 v[4:7], v[156:159], v[200:203], v[4:7]
	v_mfma_f32_16x16x32_bf16 v[0:3], v[164:167], v[200:203], v[0:3]
	v_mfma_f32_16x16x32_bf16 v[52:55], v[160:163], v[176:179], v[52:55]
	v_mfma_f32_16x16x32_bf16 v[44:47], v[168:171], v[176:179], v[44:47]
	v_mfma_f32_16x16x32_bf16 v[36:39], v[160:163], v[188:191], v[36:39]
	v_mfma_f32_16x16x32_bf16 v[32:35], v[168:171], v[188:191], v[32:35]
	v_mfma_f32_16x16x32_bf16 v[20:23], v[160:163], v[196:199], v[20:23]
	v_mfma_f32_16x16x32_bf16 v[12:15], v[168:171], v[196:199], v[12:15]
	v_mfma_f32_16x16x32_bf16 v[4:7], v[160:163], v[204:207], v[4:7]
	v_mfma_f32_16x16x32_bf16 v[0:3], v[168:171], v[204:207], v[0:3]
	s_setprio 0
	s_barrier
	s_add_i32 s55, 0, 0x18000
	s_add_i32 s56, 0, 0x1c000
	v_add_u32_e32 v152, s55, v138
	v_add_u32_e32 v168, s56, v138
	ds_read_b128 v[140:143], v152
	ds_read_b128 v[144:147], v152 offset:1024
	ds_read_b128 v[148:151], v152 offset:2048
	ds_read_b128 v[152:155], v152 offset:3072
	ds_read_b128 v[156:159], v168
	ds_read_b128 v[160:163], v168 offset:1024
	ds_read_b128 v[164:167], v168 offset:2048
	ds_read_b128 v[168:171], v168 offset:3072
	s_add_u32 s22, s22, 0x100000
	s_addc_u32 s23, s23, 0
	s_mov_b32 m0, s45
	ds_read_b128 v[172:175], v139 offset:32768
	ds_read_b128 v[176:179], v139 offset:33792
	ds_read_b128 v[184:187], v139 offset:34816
	ds_read_b128 v[188:191], v139 offset:35840
	ds_read_b128 v[192:195], v139 offset:36864
	ds_read_b128 v[196:199], v139 offset:37888
	ds_read_b128 v[200:203], v139 offset:38912
	ds_read_b128 v[204:207], v139 offset:39936
	global_load_lds_dwordx4 v132, s[22:23]
	s_mov_b32 m0, s46
	s_nop 0
	global_load_lds_dwordx4 v130, s[22:23]
	s_waitcnt vmcnt(8)
	s_waitcnt lgkmcnt(0)
	s_barrier
	s_setprio 1
	s_waitcnt lgkmcnt(0)
	v_mfma_f32_16x16x32_bf16 v[124:127], v[140:143], v[172:175], v[124:127]
	v_mfma_f32_16x16x32_bf16 v[120:123], v[148:151], v[172:175], v[120:123]
	v_mfma_f32_16x16x32_bf16 v[116:119], v[140:143], v[184:187], v[116:119]
	v_mfma_f32_16x16x32_bf16 v[112:115], v[148:151], v[184:187], v[112:115]
	v_mfma_f32_16x16x32_bf16 v[92:95], v[140:143], v[192:195], v[92:95]
	v_mfma_f32_16x16x32_bf16 v[88:91], v[148:151], v[192:195], v[88:91]
	v_mfma_f32_16x16x32_bf16 v[80:83], v[140:143], v[200:203], v[80:83]
	v_mfma_f32_16x16x32_bf16 v[72:75], v[148:151], v[200:203], v[72:75]
	v_mfma_f32_16x16x32_bf16 v[124:127], v[144:147], v[176:179], v[124:127]
	v_mfma_f32_16x16x32_bf16 v[120:123], v[152:155], v[176:179], v[120:123]
	v_mfma_f32_16x16x32_bf16 v[116:119], v[144:147], v[188:191], v[116:119]
	v_mfma_f32_16x16x32_bf16 v[112:115], v[152:155], v[188:191], v[112:115]
	v_mfma_f32_16x16x32_bf16 v[92:95], v[144:147], v[196:199], v[92:95]
	v_mfma_f32_16x16x32_bf16 v[88:91], v[152:155], v[196:199], v[88:91]
	v_mfma_f32_16x16x32_bf16 v[80:83], v[144:147], v[204:207], v[80:83]
	v_mfma_f32_16x16x32_bf16 v[72:75], v[152:155], v[204:207], v[72:75]


	v_mfma_f32_16x16x32_bf16 v[108:111], v[156:159], v[172:175], v[108:111]
	v_mfma_f32_16x16x32_bf16 v[104:107], v[164:167], v[172:175], v[104:107]
	v_mfma_f32_16x16x32_bf16 v[100:103], v[156:159], v[184:187], v[100:103]
	v_mfma_f32_16x16x32_bf16 v[96:99], v[164:167], v[184:187], v[96:99]
	v_mfma_f32_16x16x32_bf16 v[84:87], v[156:159], v[192:195], v[84:87]
	v_mfma_f32_16x16x32_bf16 v[76:79], v[164:167], v[192:195], v[76:79]
	v_mfma_f32_16x16x32_bf16 v[68:71], v[156:159], v[200:203], v[68:71]
	v_mfma_f32_16x16x32_bf16 v[64:67], v[164:167], v[200:203], v[64:67]
	v_mfma_f32_16x16x32_bf16 v[108:111], v[160:163], v[176:179], v[108:111]
	v_mfma_f32_16x16x32_bf16 v[104:107], v[168:171], v[176:179], v[104:107]
	v_mfma_f32_16x16x32_bf16 v[100:103], v[160:163], v[188:191], v[100:103]
	v_mfma_f32_16x16x32_bf16 v[96:99], v[168:171], v[188:191], v[96:99]
	v_mfma_f32_16x16x32_bf16 v[84:87], v[160:163], v[196:199], v[84:87]
	v_mfma_f32_16x16x32_bf16 v[76:79], v[168:171], v[196:199], v[76:79]
	v_mfma_f32_16x16x32_bf16 v[68:71], v[160:163], v[204:207], v[68:71]
	v_mfma_f32_16x16x32_bf16 v[64:67], v[168:171], v[204:207], v[64:67]
	s_setprio 0
	s_barrier
	s_add_i32 s22, s55, s42
	s_mov_b32 m0, s22
	ds_read_b128 v[172:175], v139 offset:49152
	ds_read_b128 v[176:179], v139 offset:50176
	ds_read_b128 v[184:187], v139 offset:51200
	ds_read_b128 v[188:191], v139 offset:52224
	ds_read_b128 v[192:195], v139 offset:53248
	ds_read_b128 v[196:199], v139 offset:54272
	ds_read_b128 v[200:203], v139 offset:55296
	ds_read_b128 v[204:207], v139 offset:56320
	global_load_lds_dwordx4 v212, s[84:85]
	s_add_i32 m0, s22, 0x2000
	s_add_u32 s20, s20, 0x100080
	s_addc_u32 s21, s21, 0
	s_add_i32 s22, s56, s42
	global_load_lds_dwordx4 v128, s[84:85]
	s_mov_b32 m0, s22
	s_nop 0
	global_load_lds_dwordx4 v212, s[20:21]
	s_add_i32 m0, s22, 0x2000
	s_nop 0
	global_load_lds_dwordx4 v128, s[20:21]
	s_mov_b32 m0, s48
	s_nop 0
	global_load_lds_dwordx4 v132, s[86:87]
	s_mov_b32 m0, s49
	s_nop 0
	global_load_lds_dwordx4 v130, s[86:87]
	s_waitcnt vmcnt(8)
	s_waitcnt lgkmcnt(0)
	s_barrier
	s_setprio 1
	s_waitcnt lgkmcnt(0)
	v_mfma_f32_16x16x32_bf16 v[60:63], v[140:143], v[172:175], v[60:63]
	v_mfma_f32_16x16x32_bf16 v[56:59], v[148:151], v[172:175], v[56:59]
	v_mfma_f32_16x16x32_bf16 v[48:51], v[140:143], v[184:187], v[48:51]
	v_mfma_f32_16x16x32_bf16 v[40:43], v[148:151], v[184:187], v[40:43]
	v_mfma_f32_16x16x32_bf16 v[28:31], v[140:143], v[192:195], v[28:31]
	v_mfma_f32_16x16x32_bf16 v[24:27], v[148:151], v[192:195], v[24:27]
	v_mfma_f32_16x16x32_bf16 v[16:19], v[140:143], v[200:203], v[16:19]
	v_mfma_f32_16x16x32_bf16 v[8:11], v[148:151], v[200:203], v[8:11]
	v_mfma_f32_16x16x32_bf16 v[60:63], v[144:147], v[176:179], v[60:63]
	v_mfma_f32_16x16x32_bf16 v[56:59], v[152:155], v[176:179], v[56:59]
	v_mfma_f32_16x16x32_bf16 v[48:51], v[144:147], v[188:191], v[48:51]
	v_mfma_f32_16x16x32_bf16 v[40:43], v[152:155], v[188:191], v[40:43]
	v_mfma_f32_16x16x32_bf16 v[28:31], v[144:147], v[196:199], v[28:31]
	v_mfma_f32_16x16x32_bf16 v[24:27], v[152:155], v[196:199], v[24:27]
	v_mfma_f32_16x16x32_bf16 v[16:19], v[144:147], v[204:207], v[16:19]
	v_mfma_f32_16x16x32_bf16 v[8:11], v[152:155], v[204:207], v[8:11]


	v_mfma_f32_16x16x32_bf16 v[52:55], v[156:159], v[172:175], v[52:55]
	v_mfma_f32_16x16x32_bf16 v[44:47], v[164:167], v[172:175], v[44:47]
	v_mfma_f32_16x16x32_bf16 v[36:39], v[156:159], v[184:187], v[36:39]
	v_mfma_f32_16x16x32_bf16 v[32:35], v[164:167], v[184:187], v[32:35]
	v_mfma_f32_16x16x32_bf16 v[20:23], v[156:159], v[192:195], v[20:23]
	v_mfma_f32_16x16x32_bf16 v[12:15], v[164:167], v[192:195], v[12:15]
	v_mfma_f32_16x16x32_bf16 v[4:7], v[156:159], v[200:203], v[4:7]
	v_mfma_f32_16x16x32_bf16 v[0:3], v[164:167], v[200:203], v[0:3]
	v_mfma_f32_16x16x32_bf16 v[52:55], v[160:163], v[176:179], v[52:55]
	v_mfma_f32_16x16x32_bf16 v[44:47], v[168:171], v[176:179], v[44:47]
	v_mfma_f32_16x16x32_bf16 v[36:39], v[160:163], v[188:191], v[36:39]
	v_mfma_f32_16x16x32_bf16 v[32:35], v[168:171], v[188:191], v[32:35]
	v_mfma_f32_16x16x32_bf16 v[20:23], v[160:163], v[196:199], v[20:23]
	v_mfma_f32_16x16x32_bf16 v[12:15], v[168:171], v[196:199], v[12:15]
	v_mfma_f32_16x16x32_bf16 v[4:7], v[160:163], v[204:207], v[4:7]
	v_mfma_f32_16x16x32_bf16 v[0:3], v[168:171], v[204:207], v[0:3]
	s_setprio 0
	s_barrier
	s_add_i32 s54, s54, 2
	s_add_u32 s18, s18, 0x100
	s_addc_u32 s19, s19, 0
	s_cmp_lt_u32 s54, 62
	s_cbranch_scc1 .LBB0_599
	s_waitcnt vmcnt(0)
	s_cmpk_gt_u32 s36, 0xff
	s_cbranch_scc1 .LBB0_602
	s_barrier
